# light phases: P7/P9 query loads hoisted, P9 sc1 output stores, P8 batched cum chain + deferred queue atomic + parallel OFFS copy
# baseline (speedup 1.0000x reference)
; #define LAS __attribute__((address_space(3)))
; template <bool ENGINE, int ESTEPS>
; __device__ __forceinline__ void moba_sparse(const Frame& F, const Args& a, int rep) {
;     ...
;         for (int i = tid; i < NBLK * OFFS_LD / 2; i += 512) ((LAS unsigned*)offs)[i] = ((const unsigned*)(OFFS + (size_t)bh * NBLK * OFFS_LD))[i];
;         if (tid == 0) { itq[0] = (int)__hip_atomic_fetch_add(qctr, 1u, RLX_AGENT); itq[1] = (int)__hip_atomic_fetch_add(qctr, 1u, RLX_AGENT); }
;         __syncthreads();
;         if (tid < 64) { const int j = tid; int acc = 0;
;             for (int qb = 0; qb < NBLK; ++qb) { cum[qb * NBLK + j] = (unsigned short)acc;
;                 if (qb > j && j < NBLK - 1) acc += (int)offs[qb * OFFS_LD + j + 1] - (int)offs[qb * OFFS_LD + j]; }
;             NJ[j] = acc;
;             const int c = (acc + SP_PART - 1) / SP_PART; int s = c;
; #pragma unroll
;             for (int o = 1; o < 64; o <<= 1) { const int t = __shfl_up(s, o); if (lane >= o) s += t; }
;             IP[j] = s - c; if (j == 63) IP[64] = s; }
.LBB0_977:
	s_mov_b64 s[4:5], 0x1000
	v_lshl_add_u64 v[242:243], v[18:19], 0, s[4:5]
	s_mov_b64 s[4:5], 0x2000
	v_lshl_add_u64 v[244:245], v[18:19], 0, s[4:5]
	global_load_dword v22, v[18:19], off
	global_load_dword v240, v[18:19], off offset:2048
	global_load_dword v241, v[242:243], off
	global_load_dword v246, v[242:243], off offset:2048
	v_cmp_gt_u32_e32 vcc, 0x80, v0
	s_and_saveexec_b64 s[0:1], vcc
	global_load_dword v247, v[244:245], off
	s_or_b64 exec, exec, s[0:1]
	s_waitcnt vmcnt(0)
	ds_write_b32 v20, v22
	ds_write_b32 v20, v240 offset:2048
	ds_write_b32 v20, v241 offset:4096
	ds_write_b32 v20, v246 offset:6144
	s_and_saveexec_b64 s[0:1], vcc
	ds_write_b32 v20, v247 offset:8192
	s_or_b64 exec, exec, s[0:1]
	s_mul_i32 s0, s57, 3
	s_add_i32 s0, s86, s0
	s_lshl_b32 s0, s0, 6
	s_ashr_i32 s1, s0, 31
	s_lshl_b64 s[0:1], s[0:1], 2
	s_add_u32 s92, s14, s0
	s_addc_u32 s93, s15, s1
	s_and_saveexec_b64 s[0:1], s[2:3]
	s_cbranch_execz .LBB0_984
	s_mov_b64 s[6:7], exec
	v_mbcnt_lo_u32_b32 v18, s6, 0
	v_mbcnt_hi_u32_b32 v18, s7, v18
	v_cmp_eq_u32_e32 vcc, 0, v18
	s_and_saveexec_b64 s[4:5], vcc
	s_cbranch_execz .LBB0_981
	s_bcnt1_i32_b64 s6, s[6:7]
	s_lshl_b32 s6, s6, 1
	v_mov_b32_e32 v19, s6
	global_atomic_add v19, v47, v19, s[92:93] sc0
.LBB0_981:
	s_or_b64 exec, exec, s[4:5]
	s_waitcnt vmcnt(0)
	v_readfirstlane_b32 s6, v19
	s_mov_b64 s[4:5], exec
	v_mov_b32_e32 v19, s16
	v_add_u32_e32 v18, s6, v18
	ds_write_b32 v19, v18
	v_add_u32_e32 v18, 1, v18
	v_mov_b32_e32 v19, s45
	ds_write_b32 v19, v18
.LBB0_984:
	s_or_b64 exec, exec, s[0:1]
	s_waitcnt lgkmcnt(0)
	s_barrier
	s_and_saveexec_b64 s[0:1], s[94:95]
	s_cbranch_execz .LBB0_1111
	v_mov_b32_e32 v18, 0
	ds_write_b16 v85, v47
	ds_write_b16 v85, v47 offset:128
	s_mov_b64 s[4:5], exec
	ds_read_u16 v240, v86 offset:138
	ds_read_u16 v241, v86 offset:136
	ds_read_u16 v242, v86 offset:274
	ds_read_u16 v243, v86 offset:272
	ds_read_u16 v244, v86 offset:410
	ds_read_u16 v245, v86 offset:408
	ds_read_u16 v246, v86 offset:546
	ds_read_u16 v247, v86 offset:544
	ds_read_u16 v248, v86 offset:682
	ds_read_u16 v249, v86 offset:680
	ds_read_u16 v250, v86 offset:818
	ds_read_u16 v251, v86 offset:816
	ds_read_u16 v252, v86 offset:954
	ds_read_u16 v253, v86 offset:952
	s_waitcnt lgkmcnt(0)
	v_cmp_gt_u32_e32 vcc, 1, v0
	v_sub_u32_e32 v19, v240, v241
	s_nop 0
	v_cndmask_b32_e32 v19, 0, v19, vcc
	v_add_u32_e32 v18, v18, v19
	ds_write_b16 v85, v18 offset:256
	v_cmp_gt_u32_e32 vcc, 2, v0
	v_sub_u32_e32 v19, v242, v243
	s_nop 0
	v_cndmask_b32_e32 v19, 0, v19, vcc
	v_add_u32_e32 v18, v18, v19
	ds_write_b16 v85, v18 offset:384
	v_cmp_gt_u32_e32 vcc, 3, v0
	v_sub_u32_e32 v19, v244, v245
	s_nop 0
	v_cndmask_b32_e32 v19, 0, v19, vcc
	v_add_u32_e32 v18, v18, v19
	ds_write_b16 v85, v18 offset:512
	v_cmp_gt_u32_e32 vcc, 4, v0
	v_sub_u32_e32 v19, v246, v247
	s_nop 0
	v_cndmask_b32_e32 v19, 0, v19, vcc
	v_add_u32_e32 v18, v18, v19
	ds_write_b16 v85, v18 offset:640
	v_cmp_gt_u32_e32 vcc, 5, v0
	v_sub_u32_e32 v19, v248, v249
	s_nop 0
	v_cndmask_b32_e32 v19, 0, v19, vcc
	v_add_u32_e32 v18, v18, v19
	ds_write_b16 v85, v18 offset:768
	v_cmp_gt_u32_e32 vcc, 6, v0
	v_sub_u32_e32 v19, v250, v251
	s_nop 0
	v_cndmask_b32_e32 v19, 0, v19, vcc
	v_add_u32_e32 v18, v18, v19
	ds_write_b16 v85, v18 offset:896
	v_cmp_gt_u32_e32 vcc, 7, v0
	v_sub_u32_e32 v19, v252, v253
	s_nop 0
	v_cndmask_b32_e32 v19, 0, v19, vcc
	v_add_u32_e32 v18, v18, v19
	ds_write_b16 v85, v18 offset:1024
	ds_read_u16 v240, v86 offset:1090
	ds_read_u16 v241, v86 offset:1088
	ds_read_u16 v242, v86 offset:1226
	ds_read_u16 v243, v86 offset:1224
	ds_read_u16 v244, v86 offset:1362
	ds_read_u16 v245, v86 offset:1360
	ds_read_u16 v246, v86 offset:1498
	ds_read_u16 v247, v86 offset:1496
	ds_read_u16 v248, v86 offset:1634
	ds_read_u16 v249, v86 offset:1632
	ds_read_u16 v250, v86 offset:1770
	ds_read_u16 v251, v86 offset:1768
	ds_read_u16 v252, v86 offset:1906
	ds_read_u16 v253, v86 offset:1904
	s_waitcnt lgkmcnt(0)
	v_cmp_gt_u32_e32 vcc, 8, v0
	v_sub_u32_e32 v19, v240, v241
	s_nop 0
	v_cndmask_b32_e32 v19, 0, v19, vcc
	v_add_u32_e32 v18, v18, v19
	ds_write_b16 v85, v18 offset:1152
	v_cmp_gt_u32_e32 vcc, 9, v0
	v_sub_u32_e32 v19, v242, v243
	s_nop 0
	v_cndmask_b32_e32 v19, 0, v19, vcc
	v_add_u32_e32 v18, v18, v19
	ds_write_b16 v85, v18 offset:1280
	v_cmp_gt_u32_e32 vcc, 10, v0
	v_sub_u32_e32 v19, v244, v245
	s_nop 0
	v_cndmask_b32_e32 v19, 0, v19, vcc
	v_add_u32_e32 v18, v18, v19
	ds_write_b16 v85, v18 offset:1408
	v_cmp_gt_u32_e32 vcc, 11, v0
	v_sub_u32_e32 v19, v246, v247
	s_nop 0
	v_cndmask_b32_e32 v19, 0, v19, vcc
	v_add_u32_e32 v18, v18, v19
	ds_write_b16 v85, v18 offset:1536
	v_cmp_gt_u32_e32 vcc, 12, v0
	v_sub_u32_e32 v19, v248, v249
	s_nop 0
	v_cndmask_b32_e32 v19, 0, v19, vcc
	v_add_u32_e32 v18, v18, v19
	ds_write_b16 v85, v18 offset:1664
	v_cmp_gt_u32_e32 vcc, 13, v0
	v_sub_u32_e32 v19, v250, v251
	s_nop 0
	v_cndmask_b32_e32 v19, 0, v19, vcc
	v_add_u32_e32 v18, v18, v19
	ds_write_b16 v85, v18 offset:1792
	v_cmp_gt_u32_e32 vcc, 14, v0
	v_sub_u32_e32 v19, v252, v253
	s_nop 0
	v_cndmask_b32_e32 v19, 0, v19, vcc
	v_add_u32_e32 v18, v18, v19
	ds_write_b16 v85, v18 offset:1920
	ds_read_u16 v240, v86 offset:2042
	ds_read_u16 v241, v86 offset:2040
	ds_read_u16 v242, v86 offset:2178
	ds_read_u16 v243, v86 offset:2176
	ds_read_u16 v244, v86 offset:2314
	ds_read_u16 v245, v86 offset:2312
	ds_read_u16 v246, v86 offset:2450
	ds_read_u16 v247, v86 offset:2448
	ds_read_u16 v248, v86 offset:2586
	ds_read_u16 v249, v86 offset:2584
	ds_read_u16 v250, v86 offset:2722
	ds_read_u16 v251, v86 offset:2720
	ds_read_u16 v252, v86 offset:2858
	ds_read_u16 v253, v86 offset:2856
	s_waitcnt lgkmcnt(0)
; template <bool ENGINE, int ESTEPS>
; __device__ __forceinline__ void moba_sparse(const Frame& F, const Args& a, int rep) {
;     ...
;         if (tid < 64) { const int j = tid; int acc = 0;
;             for (int qb = 0; qb < NBLK; ++qb) { cum[qb * NBLK + j] = (unsigned short)acc;
;                 if (qb > j && j < NBLK - 1) acc += (int)offs[qb * OFFS_LD + j + 1] - (int)offs[qb * OFFS_LD + j]; }
;             NJ[j] = acc;
	v_cmp_gt_u32_e32 vcc, 15, v0
	v_sub_u32_e32 v19, v240, v241
	s_nop 0
	v_cndmask_b32_e32 v19, 0, v19, vcc
	v_add_u32_e32 v18, v18, v19
	ds_write_b16 v85, v18 offset:2048
	v_cmp_gt_u32_e32 vcc, 16, v0
	v_sub_u32_e32 v19, v242, v243
	s_nop 0
	v_cndmask_b32_e32 v19, 0, v19, vcc
	v_add_u32_e32 v18, v18, v19
	ds_write_b16 v85, v18 offset:2176
	v_cmp_gt_u32_e32 vcc, 17, v0
	v_sub_u32_e32 v19, v244, v245
	s_nop 0
	v_cndmask_b32_e32 v19, 0, v19, vcc
	v_add_u32_e32 v18, v18, v19
	ds_write_b16 v85, v18 offset:2304
	v_cmp_gt_u32_e32 vcc, 18, v0
	v_sub_u32_e32 v19, v246, v247
	s_nop 0
	v_cndmask_b32_e32 v19, 0, v19, vcc
	v_add_u32_e32 v18, v18, v19
	ds_write_b16 v85, v18 offset:2432
	v_cmp_gt_u32_e32 vcc, 19, v0
	v_sub_u32_e32 v19, v248, v249
	s_nop 0
	v_cndmask_b32_e32 v19, 0, v19, vcc
	v_add_u32_e32 v18, v18, v19
	ds_write_b16 v85, v18 offset:2560
	v_cmp_gt_u32_e32 vcc, 20, v0
	v_sub_u32_e32 v19, v250, v251
	s_nop 0
	v_cndmask_b32_e32 v19, 0, v19, vcc
	v_add_u32_e32 v18, v18, v19
	ds_write_b16 v85, v18 offset:2688
	v_cmp_gt_u32_e32 vcc, 21, v0
	v_sub_u32_e32 v19, v252, v253
	s_nop 0
	v_cndmask_b32_e32 v19, 0, v19, vcc
	v_add_u32_e32 v18, v18, v19
	ds_write_b16 v85, v18 offset:2816
	ds_read_u16 v240, v86 offset:2994
	ds_read_u16 v241, v86 offset:2992
	ds_read_u16 v242, v86 offset:3130
	ds_read_u16 v243, v86 offset:3128
	ds_read_u16 v244, v86 offset:3266
	ds_read_u16 v245, v86 offset:3264
	ds_read_u16 v246, v86 offset:3402
	ds_read_u16 v247, v86 offset:3400
	ds_read_u16 v248, v86 offset:3538
	ds_read_u16 v249, v86 offset:3536
	ds_read_u16 v250, v86 offset:3674
	ds_read_u16 v251, v86 offset:3672
	ds_read_u16 v252, v86 offset:3810
	ds_read_u16 v253, v86 offset:3808
	s_waitcnt lgkmcnt(0)
	v_cmp_gt_u32_e32 vcc, 22, v0
	v_sub_u32_e32 v19, v240, v241
	s_nop 0
	v_cndmask_b32_e32 v19, 0, v19, vcc
	v_add_u32_e32 v18, v18, v19
	ds_write_b16 v85, v18 offset:2944
	v_cmp_gt_u32_e32 vcc, 23, v0
	v_sub_u32_e32 v19, v242, v243
	s_nop 0
	v_cndmask_b32_e32 v19, 0, v19, vcc
	v_add_u32_e32 v18, v18, v19
	ds_write_b16 v85, v18 offset:3072
	v_cmp_gt_u32_e32 vcc, 24, v0
	v_sub_u32_e32 v19, v244, v245
	s_nop 0
	v_cndmask_b32_e32 v19, 0, v19, vcc
	v_add_u32_e32 v18, v18, v19
	ds_write_b16 v85, v18 offset:3200
	v_cmp_gt_u32_e32 vcc, 25, v0
	v_sub_u32_e32 v19, v246, v247
	s_nop 0
	v_cndmask_b32_e32 v19, 0, v19, vcc
	v_add_u32_e32 v18, v18, v19
	ds_write_b16 v85, v18 offset:3328
	v_cmp_gt_u32_e32 vcc, 26, v0
	v_sub_u32_e32 v19, v248, v249
	s_nop 0
	v_cndmask_b32_e32 v19, 0, v19, vcc
	v_add_u32_e32 v18, v18, v19
	ds_write_b16 v85, v18 offset:3456
	v_cmp_gt_u32_e32 vcc, 27, v0
	v_sub_u32_e32 v19, v250, v251
	s_nop 0
	v_cndmask_b32_e32 v19, 0, v19, vcc
	v_add_u32_e32 v18, v18, v19
	ds_write_b16 v85, v18 offset:3584
	v_cmp_gt_u32_e32 vcc, 28, v0
	v_sub_u32_e32 v19, v252, v253
	s_nop 0
	v_cndmask_b32_e32 v19, 0, v19, vcc
	v_add_u32_e32 v18, v18, v19
	ds_write_b16 v85, v18 offset:3712
	ds_read_u16 v240, v86 offset:3946
	ds_read_u16 v241, v86 offset:3944
	ds_read_u16 v242, v86 offset:4082
	ds_read_u16 v243, v86 offset:4080
	ds_read_u16 v244, v86 offset:4218
	ds_read_u16 v245, v86 offset:4216
	ds_read_u16 v246, v86 offset:4354
	ds_read_u16 v247, v86 offset:4352
	ds_read_u16 v248, v86 offset:4490
	ds_read_u16 v249, v86 offset:4488
	ds_read_u16 v250, v86 offset:4626
	ds_read_u16 v251, v86 offset:4624
	ds_read_u16 v252, v86 offset:4762
	ds_read_u16 v253, v86 offset:4760
	s_waitcnt lgkmcnt(0)
	v_cmp_gt_u32_e32 vcc, 29, v0
	v_sub_u32_e32 v19, v240, v241
	s_nop 0
	v_cndmask_b32_e32 v19, 0, v19, vcc
	v_add_u32_e32 v18, v18, v19
	ds_write_b16 v85, v18 offset:3840
	v_cmp_gt_u32_e32 vcc, 30, v0
	v_sub_u32_e32 v19, v242, v243
	s_nop 0
	v_cndmask_b32_e32 v19, 0, v19, vcc
	v_add_u32_e32 v18, v18, v19
	ds_write_b16 v85, v18 offset:3968
	v_cmp_gt_u32_e32 vcc, 31, v0
	v_sub_u32_e32 v19, v244, v245
	s_nop 0
	v_cndmask_b32_e32 v19, 0, v19, vcc
	v_add_u32_e32 v18, v18, v19
	ds_write_b16 v85, v18 offset:4096
	v_cmp_gt_u32_e32 vcc, 32, v0
	v_sub_u32_e32 v19, v246, v247
	s_nop 0
	v_cndmask_b32_e32 v19, 0, v19, vcc
	v_add_u32_e32 v18, v18, v19
	ds_write_b16 v85, v18 offset:4224
	v_cmp_gt_u32_e32 vcc, 33, v0
	v_sub_u32_e32 v19, v248, v249
	s_nop 0
	v_cndmask_b32_e32 v19, 0, v19, vcc
	v_add_u32_e32 v18, v18, v19
	ds_write_b16 v85, v18 offset:4352
	v_cmp_gt_u32_e32 vcc, 34, v0
	v_sub_u32_e32 v19, v250, v251
	s_nop 0
	v_cndmask_b32_e32 v19, 0, v19, vcc
	v_add_u32_e32 v18, v18, v19
	ds_write_b16 v85, v18 offset:4480
	v_cmp_gt_u32_e32 vcc, 35, v0
	v_sub_u32_e32 v19, v252, v253
	s_nop 0
	v_cndmask_b32_e32 v19, 0, v19, vcc
	v_add_u32_e32 v18, v18, v19
	ds_write_b16 v85, v18 offset:4608
	ds_read_u16 v240, v86 offset:4898
	ds_read_u16 v241, v86 offset:4896
	ds_read_u16 v242, v86 offset:5034
	ds_read_u16 v243, v86 offset:5032
	ds_read_u16 v244, v86 offset:5170
	ds_read_u16 v245, v86 offset:5168
	ds_read_u16 v246, v86 offset:5306
	ds_read_u16 v247, v86 offset:5304
	ds_read_u16 v248, v86 offset:5442
	ds_read_u16 v249, v86 offset:5440
	ds_read_u16 v250, v86 offset:5578
	ds_read_u16 v251, v86 offset:5576
	ds_read_u16 v252, v86 offset:5714
	ds_read_u16 v253, v86 offset:5712
	s_waitcnt lgkmcnt(0)
; template <bool ENGINE, int ESTEPS>
; __device__ __forceinline__ void moba_sparse(const Frame& F, const Args& a, int rep) {
;     ...
;         if (tid < 64) { const int j = tid; int acc = 0;
;             for (int qb = 0; qb < NBLK; ++qb) { cum[qb * NBLK + j] = (unsigned short)acc;
;                 if (qb > j && j < NBLK - 1) acc += (int)offs[qb * OFFS_LD + j + 1] - (int)offs[qb * OFFS_LD + j]; }
;             NJ[j] = acc;
	v_cmp_gt_u32_e32 vcc, 36, v0
	v_sub_u32_e32 v19, v240, v241
	s_nop 0
	v_cndmask_b32_e32 v19, 0, v19, vcc
	v_add_u32_e32 v18, v18, v19
	ds_write_b16 v85, v18 offset:4736
	v_cmp_gt_u32_e32 vcc, 37, v0
	v_sub_u32_e32 v19, v242, v243
	s_nop 0
	v_cndmask_b32_e32 v19, 0, v19, vcc
	v_add_u32_e32 v18, v18, v19
	ds_write_b16 v85, v18 offset:4864
	v_cmp_gt_u32_e32 vcc, 38, v0
	v_sub_u32_e32 v19, v244, v245
	s_nop 0
	v_cndmask_b32_e32 v19, 0, v19, vcc
	v_add_u32_e32 v18, v18, v19
	ds_write_b16 v85, v18 offset:4992
	v_cmp_gt_u32_e32 vcc, 39, v0
	v_sub_u32_e32 v19, v246, v247
	s_nop 0
	v_cndmask_b32_e32 v19, 0, v19, vcc
	v_add_u32_e32 v18, v18, v19
	ds_write_b16 v85, v18 offset:5120
	v_cmp_gt_u32_e32 vcc, 40, v0
	v_sub_u32_e32 v19, v248, v249
	s_nop 0
	v_cndmask_b32_e32 v19, 0, v19, vcc
	v_add_u32_e32 v18, v18, v19
	ds_write_b16 v85, v18 offset:5248
	v_cmp_gt_u32_e32 vcc, 41, v0
	v_sub_u32_e32 v19, v250, v251
	s_nop 0
	v_cndmask_b32_e32 v19, 0, v19, vcc
	v_add_u32_e32 v18, v18, v19
	ds_write_b16 v85, v18 offset:5376
	v_cmp_gt_u32_e32 vcc, 42, v0
	v_sub_u32_e32 v19, v252, v253
	s_nop 0
	v_cndmask_b32_e32 v19, 0, v19, vcc
	v_add_u32_e32 v18, v18, v19
	ds_write_b16 v85, v18 offset:5504
	ds_read_u16 v240, v86 offset:5850
	ds_read_u16 v241, v86 offset:5848
	ds_read_u16 v242, v86 offset:5986
	ds_read_u16 v243, v86 offset:5984
	ds_read_u16 v244, v86 offset:6122
	ds_read_u16 v245, v86 offset:6120
	ds_read_u16 v246, v86 offset:6258
	ds_read_u16 v247, v86 offset:6256
	ds_read_u16 v248, v86 offset:6394
	ds_read_u16 v249, v86 offset:6392
	ds_read_u16 v250, v86 offset:6530
	ds_read_u16 v251, v86 offset:6528
	ds_read_u16 v252, v86 offset:6666
	ds_read_u16 v253, v86 offset:6664
	s_waitcnt lgkmcnt(0)
	v_cmp_gt_u32_e32 vcc, 43, v0
	v_sub_u32_e32 v19, v240, v241
	s_nop 0
	v_cndmask_b32_e32 v19, 0, v19, vcc
	v_add_u32_e32 v18, v18, v19
	ds_write_b16 v85, v18 offset:5632
	v_cmp_gt_u32_e32 vcc, 44, v0
	v_sub_u32_e32 v19, v242, v243
	s_nop 0
	v_cndmask_b32_e32 v19, 0, v19, vcc
	v_add_u32_e32 v18, v18, v19
	ds_write_b16 v85, v18 offset:5760
	v_cmp_gt_u32_e32 vcc, 45, v0
	v_sub_u32_e32 v19, v244, v245
	s_nop 0
	v_cndmask_b32_e32 v19, 0, v19, vcc
	v_add_u32_e32 v18, v18, v19
	ds_write_b16 v85, v18 offset:5888
	v_cmp_gt_u32_e32 vcc, 46, v0
	v_sub_u32_e32 v19, v246, v247
	s_nop 0
	v_cndmask_b32_e32 v19, 0, v19, vcc
	v_add_u32_e32 v18, v18, v19
	ds_write_b16 v85, v18 offset:6016
	v_cmp_gt_u32_e32 vcc, 47, v0
	v_sub_u32_e32 v19, v248, v249
	s_nop 0
	v_cndmask_b32_e32 v19, 0, v19, vcc
	v_add_u32_e32 v18, v18, v19
	ds_write_b16 v85, v18 offset:6144
	v_cmp_gt_u32_e32 vcc, 48, v0
	v_sub_u32_e32 v19, v250, v251
	s_nop 0
	v_cndmask_b32_e32 v19, 0, v19, vcc
	v_add_u32_e32 v18, v18, v19
	ds_write_b16 v85, v18 offset:6272
	v_cmp_gt_u32_e32 vcc, 49, v0
	v_sub_u32_e32 v19, v252, v253
	s_nop 0
	v_cndmask_b32_e32 v19, 0, v19, vcc
	v_add_u32_e32 v18, v18, v19
	ds_write_b16 v85, v18 offset:6400
	ds_read_u16 v240, v86 offset:6802
	ds_read_u16 v241, v86 offset:6800
	ds_read_u16 v242, v86 offset:6938
	ds_read_u16 v243, v86 offset:6936
	ds_read_u16 v244, v86 offset:7074
	ds_read_u16 v245, v86 offset:7072
	ds_read_u16 v246, v86 offset:7210
	ds_read_u16 v247, v86 offset:7208
	ds_read_u16 v248, v86 offset:7346
	ds_read_u16 v249, v86 offset:7344
	ds_read_u16 v250, v86 offset:7482
	ds_read_u16 v251, v86 offset:7480
	ds_read_u16 v252, v86 offset:7618
	ds_read_u16 v253, v86 offset:7616
	s_waitcnt lgkmcnt(0)
	v_cmp_gt_u32_e32 vcc, 50, v0
	v_sub_u32_e32 v19, v240, v241
	s_nop 0
	v_cndmask_b32_e32 v19, 0, v19, vcc
	v_add_u32_e32 v18, v18, v19
	ds_write_b16 v85, v18 offset:6528
	v_cmp_gt_u32_e32 vcc, 51, v0
	v_sub_u32_e32 v19, v242, v243
	s_nop 0
	v_cndmask_b32_e32 v19, 0, v19, vcc
	v_add_u32_e32 v18, v18, v19
	ds_write_b16 v85, v18 offset:6656
	v_cmp_gt_u32_e32 vcc, 52, v0
	v_sub_u32_e32 v19, v244, v245
	s_nop 0
	v_cndmask_b32_e32 v19, 0, v19, vcc
	v_add_u32_e32 v18, v18, v19
	ds_write_b16 v85, v18 offset:6784
	v_cmp_gt_u32_e32 vcc, 53, v0
	v_sub_u32_e32 v19, v246, v247
	s_nop 0
	v_cndmask_b32_e32 v19, 0, v19, vcc
	v_add_u32_e32 v18, v18, v19
	ds_write_b16 v85, v18 offset:6912
	v_cmp_gt_u32_e32 vcc, 54, v0
	v_sub_u32_e32 v19, v248, v249
	s_nop 0
	v_cndmask_b32_e32 v19, 0, v19, vcc
	v_add_u32_e32 v18, v18, v19
	ds_write_b16 v85, v18 offset:7040
	v_cmp_gt_u32_e32 vcc, 55, v0
	v_sub_u32_e32 v19, v250, v251
	s_nop 0
	v_cndmask_b32_e32 v19, 0, v19, vcc
	v_add_u32_e32 v18, v18, v19
	ds_write_b16 v85, v18 offset:7168
	v_cmp_gt_u32_e32 vcc, 56, v0
	v_sub_u32_e32 v19, v252, v253
	s_nop 0
	v_cndmask_b32_e32 v19, 0, v19, vcc
	v_add_u32_e32 v18, v18, v19
	ds_write_b16 v85, v18 offset:7296
	ds_read_u16 v240, v86 offset:7754
	ds_read_u16 v241, v86 offset:7752
	ds_read_u16 v242, v86 offset:7890
	ds_read_u16 v243, v86 offset:7888
	ds_read_u16 v244, v86 offset:8026
	ds_read_u16 v245, v86 offset:8024
	ds_read_u16 v246, v86 offset:8162
	ds_read_u16 v247, v86 offset:8160
	ds_read_u16 v248, v86 offset:8298
	ds_read_u16 v249, v86 offset:8296
	ds_read_u16 v250, v86 offset:8434
	ds_read_u16 v251, v86 offset:8432
	ds_read_u16 v252, v86 offset:8570
	ds_read_u16 v253, v86 offset:8568
	s_waitcnt lgkmcnt(0)
	v_cmp_gt_u32_e32 vcc, 57, v0
	v_sub_u32_e32 v19, v240, v241
	s_nop 0
	v_cndmask_b32_e32 v19, 0, v19, vcc
	v_add_u32_e32 v18, v18, v19
	ds_write_b16 v85, v18 offset:7424
	v_cmp_gt_u32_e32 vcc, 58, v0
	v_sub_u32_e32 v19, v242, v243
	s_nop 0
	v_cndmask_b32_e32 v19, 0, v19, vcc
	v_add_u32_e32 v18, v18, v19
	ds_write_b16 v85, v18 offset:7552
	v_cmp_gt_u32_e32 vcc, 59, v0
	v_sub_u32_e32 v19, v244, v245
	s_nop 0
	v_cndmask_b32_e32 v19, 0, v19, vcc
	v_add_u32_e32 v18, v18, v19
	ds_write_b16 v85, v18 offset:7680
	v_cmp_gt_u32_e32 vcc, 60, v0
	v_sub_u32_e32 v19, v246, v247
	s_nop 0
	v_cndmask_b32_e32 v19, 0, v19, vcc
	v_add_u32_e32 v18, v18, v19
	ds_write_b16 v85, v18 offset:7808
	v_cmp_gt_u32_e32 vcc, 61, v0
	v_sub_u32_e32 v19, v248, v249
	s_nop 0
	v_cndmask_b32_e32 v19, 0, v19, vcc
	v_add_u32_e32 v18, v18, v19
	ds_write_b16 v85, v18 offset:7936
	v_cmp_gt_u32_e32 vcc, 62, v0
	v_sub_u32_e32 v19, v250, v251
	s_nop 0
	v_cndmask_b32_e32 v19, 0, v19, vcc
	v_add_u32_e32 v18, v18, v19
	ds_write_b16 v85, v18 offset:8064
	v_cmp_gt_u32_e32 vcc, 63, v0
	v_sub_u32_e32 v19, v252, v253
	s_nop 0
	v_cndmask_b32_e32 v19, 0, v19, vcc
	v_add_u32_e32 v18, v18, v19

; #define LAS __attribute__((address_space(3)))
; template <bool ENGINE, int ESTEPS>
; __device__ __forceinline__ void moba_sparse(const Frame& F, const Args& a, int rep) {
;     ...
;             if (iter > 0) { it_cur = it_nxt; it_nxt = itq[0]; }
;             if (it_cur >= TI) break;
;             LAS const unsigned char* Kimg = F.lds + cb * 65536; LAS const unsigned char* Vimg = Kimg + 32768;
;             unsigned nn = 0u; if (tid == 0) nn = __hip_atomic_fetch_add(qctr, 1u, RLX_AGENT);
;             const int npairs = nw0 <= 0 ? 0 : (nw1 > 0 ? 2 : 1); bool done_pf = false;
.LBB0_1131:
	v_mov_b32_e32 v103, 0
	s_and_saveexec_b64 s[8:9], s[2:3]
	s_cbranch_execz .LBB0_1135
	s_mov_b64 s[54:55], exec
	v_mbcnt_lo_u32_b32 v20, s54, 0
	v_mbcnt_hi_u32_b32 v20, s55, v20
	v_cmp_eq_u32_e32 vcc, 0, v20
	s_and_saveexec_b64 s[52:53], vcc
	s_cbranch_execz .LBB0_1134
	s_bcnt1_i32_b64 s34, s[54:55]
	v_mov_b32_e32 v240, s34
	global_atomic_add v240, v47, v240, s[92:93] sc0
.LBB0_1134:
	s_or_b64 exec, exec, s[52:53]
	v_mov_b32_e32 v241, v20

; #define LAS __attribute__((address_space(3)))
; template <bool ENGINE, int ESTEPS>
; __device__ __forceinline__ void moba_sparse(const Frame& F, const Args& a, int rep) {
;     ...
;             unsigned ea = 0u, eb = 0u; h16x8 ra0, ra1, rb0, rb1;
;             if (nw0 > 0) { ea = (unsigned)__shfl((int)ment, fr < nw0 ? fr : nw0 - 1); eb = (unsigned)__shfl((int)ment, 16 + fr < nw0 ? 16 + fr : nw0 - 1);
;                 const f16_t* pa = P + (size_t)(b * SEQ + (int)(ea >> 2)) * NB + h * HD + 8 * G; const f16_t* pb = P + (size_t)(b * SEQ + (int)(eb >> 2)) * NB + h * HD + 8 * G;
;                 ra0 = *(const h16x8*)pa; ra1 = *(const h16x8*)(pa + 32); rb0 = *(const h16x8*)pb; rb1 = *(const h16x8*)(pb + 32); }
;             __syncthreads();
;             if (iter > 0) { it_cur = it_nxt; it_nxt = itq[0]; }
;             if (it_cur >= TI) break;
;             LAS const unsigned char* Kimg = F.lds + cb * 65536; LAS const unsigned char* Vimg = Kimg + 32768;
;             unsigned nn = 0u; if (tid == 0) nn = __hip_atomic_fetch_add(qctr, 1u, RLX_AGENT);
;             const int npairs = nw0 <= 0 ? 0 : (nw1 > 0 ? 2 : 1); bool done_pf = false;
;             for (int k = 0; k < npairs; ++k) {
;                 const int nwk = k ? nw1 : nw0;
;                 const bool va = fr < nwk, vb = 16 + fr < nwk; const unsigned cea = ea, ceb = eb;
;                 const int ta = (int)(cea >> 2), tb = (int)(ceb >> 2);
;                 h16x8 qa0, qa1, qb0, qb1; float mba, mbb;
;                 moba_finish_q(ra0, ra1, maxgk, qa0, qa1, mba); moba_finish_q(rb0, rb1, maxgk, qb0, qb1, mbb);
.LBB0_1137:
	s_cmp_lg_u64 s[2:3], 0
	s_cbranch_scc0 .Lp8_w_all
	s_waitcnt vmcnt(1)
	s_branch .Lp8_pair_top

; __device__ __forceinline__ void moba_finish_q(h16x8 r0v, h16x8 r1v, float maxgk, h16x8& q0, h16x8& q1, float& mb) {
;     float q[16], n2 = 0.f;
; #pragma unroll
;     for (int j = 0; j < 8; ++j) { q[j] = (float)r0v[j]; q[8 + j] = (float)r1v[j]; n2 += q[j] * q[j] + q[8 + j] * q[8 + j]; }
;     n2 += __shfl_xor(n2, 16); n2 += __shfl_xor(n2, 32);
;     mb = (sqrtf(n2) * maxgk - BOUND_SHIFT) * LOG2E;
.Lp8_pair_top:
	v_cvt_f32_f16_sdwa v25, v6 dst_sel:DWORD dst_unused:UNUSED_PAD src0_sel:WORD_1
	v_cvt_f32_f16_e32 v24, v6
	v_cvt_f32_f16_sdwa v21, v2 dst_sel:DWORD dst_unused:UNUSED_PAD src0_sel:WORD_1
	v_cvt_f32_f16_e32 v20, v2
	v_cvt_f32_f16_sdwa v37, v7 dst_sel:DWORD dst_unused:UNUSED_PAD src0_sel:WORD_1
	v_cvt_f32_f16_e32 v36, v7
	v_cvt_f32_f16_sdwa v23, v3 dst_sel:DWORD dst_unused:UNUSED_PAD src0_sel:WORD_1
	v_cvt_f32_f16_e32 v22, v3
	v_cvt_f32_f16_sdwa v31, v8 dst_sel:DWORD dst_unused:UNUSED_PAD src0_sel:WORD_1
	v_cvt_f32_f16_e32 v30, v8
	v_cvt_f32_f16_sdwa v29, v4 dst_sel:DWORD dst_unused:UNUSED_PAD src0_sel:WORD_1
	v_cvt_f32_f16_e32 v28, v4
	v_pk_mul_f32 v[26:27], v[24:25], v[24:25]
	v_pk_mul_f32 v[38:39], v[36:37], v[36:37]
	v_pk_fma_f32 v[34:35], v[20:21], v[20:21], v[26:27]
	v_cvt_f32_f16_sdwa v27, v9 dst_sel:DWORD dst_unused:UNUSED_PAD src0_sel:WORD_1
	v_cvt_f32_f16_e32 v26, v9
	v_cvt_f32_f16_sdwa v33, v5 dst_sel:DWORD dst_unused:UNUSED_PAD src0_sel:WORD_1
	v_cvt_f32_f16_e32 v32, v5
	v_pk_fma_f32 v[38:39], v[22:23], v[22:23], v[38:39]
	v_add_f32_e32 v34, v34, v35
	v_pk_mul_f32 v[40:41], v[30:31], v[30:31]
	v_add_f32_e32 v34, v38, v34
	v_pk_fma_f32 v[40:41], v[28:29], v[28:29], v[40:41]
	v_add_f32_e32 v34, v39, v34
	v_pk_mul_f32 v[42:43], v[26:27], v[26:27]
	v_add_f32_e32 v34, v40, v34
	v_pk_fma_f32 v[42:43], v[32:33], v[32:33], v[42:43]
	v_add_f32_e32 v34, v41, v34
	v_add_f32_e32 v34, v42, v34
	v_add_f32_e32 v46, v43, v34
	v_cvt_f32_f16_sdwa v43, v14 dst_sel:DWORD dst_unused:UNUSED_PAD src0_sel:WORD_1
	v_cvt_f32_f16_e32 v42, v14
	v_cvt_f32_f16_sdwa v39, v10 dst_sel:DWORD dst_unused:UNUSED_PAD src0_sel:WORD_1
	v_cvt_f32_f16_e32 v38, v10
	v_cvt_f32_f16_sdwa v75, v15 dst_sel:DWORD dst_unused:UNUSED_PAD src0_sel:WORD_1
	v_cvt_f32_f16_e32 v74, v15
	v_cvt_f32_f16_sdwa v41, v11 dst_sel:DWORD dst_unused:UNUSED_PAD src0_sel:WORD_1
	v_cvt_f32_f16_e32 v40, v11
	v_cvt_f32_f16_sdwa v71, v16 dst_sel:DWORD dst_unused:UNUSED_PAD src0_sel:WORD_1
	v_cvt_f32_f16_e32 v70, v16
	v_cvt_f32_f16_sdwa v45, v12 dst_sel:DWORD dst_unused:UNUSED_PAD src0_sel:WORD_1
	v_cvt_f32_f16_e32 v44, v12
	v_pk_mul_f32 v[34:35], v[42:43], v[42:43]
	v_pk_mul_f32 v[116:117], v[74:75], v[74:75]
	v_pk_fma_f32 v[68:69], v[38:39], v[38:39], v[34:35]
	v_cvt_f32_f16_sdwa v35, v17 dst_sel:DWORD dst_unused:UNUSED_PAD src0_sel:WORD_1
	v_cvt_f32_f16_e32 v34, v17
	v_cvt_f32_f16_sdwa v73, v13 dst_sel:DWORD dst_unused:UNUSED_PAD src0_sel:WORD_1
	v_cvt_f32_f16_e32 v72, v13
	v_pk_fma_f32 v[116:117], v[40:41], v[40:41], v[116:117]
	v_add_f32_e32 v68, v68, v69
	v_pk_mul_f32 v[118:119], v[70:71], v[70:71]
	v_add_f32_e32 v68, v116, v68
	v_pk_fma_f32 v[118:119], v[44:45], v[44:45], v[118:119]
	v_add_f32_e32 v68, v117, v68
	v_pk_mul_f32 v[120:121], v[34:35], v[34:35]
	v_add_f32_e32 v68, v118, v68
	v_pk_fma_f32 v[120:121], v[72:73], v[72:73], v[120:121]
	v_add_f32_e32 v68, v119, v68
	v_add_f32_e32 v68, v120, v68
	v_add_f32_e32 v68, v121, v68
	ds_bpermute_b32 v115, v89, v46
	ds_bpermute_b32 v69, v89, v68
	s_add_i32 s39, s69, 1
	s_mov_b64 s[8:9], -1
	s_cmp_le_u32 s36, s39
	s_waitcnt lgkmcnt(1)
	v_add_f32_e32 v119, v46, v115
	s_waitcnt lgkmcnt(0)
	v_add_f32_e32 v117, v68, v69
	ds_bpermute_b32 v120, v91, v119
	ds_bpermute_b32 v118, v91, v117
	v_readfirstlane_b32 s40, v0
	s_mov_b64 s[54:55], -1
	s_cbranch_scc0 .LBB0_1147
	s_andn2_b64 vcc, exec, s[6:7]
	v_mov_b32_e32 v69, v19
	v_mov_b32_e32 v68, v18
	s_mov_b32 s40, s41
	s_cbranch_vccnz .LBB0_1146
	s_mov_b32 s40, 64
	s_mov_b32 s70, 0

; __device__ __forceinline__ unsigned pkh(float lo, float hi) { f32x2 v = {lo, hi}; h16x2 h = __builtin_convertvector(v, h16x2); return __builtin_bit_cast(unsigned, h); }
; __device__ __forceinline__ void moba_finish_q(h16x8 r0v, h16x8 r1v, float maxgk, h16x8& q0, h16x8& q1, float& mb) {
;     ...
;     mb = (sqrtf(n2) * maxgk - BOUND_SHIFT) * LOG2E;
;     const float c = 0.125f * LOG2E;
;     u32x4 w0, w1;
;     w0.x = pkh(q[0] * c, q[1] * c); w0.y = pkh(q[2] * c, q[3] * c); w0.z = pkh(q[4] * c, q[5] * c); w0.w = pkh(q[6] * c, q[7] * c);
;     w1.x = pkh(q[8] * c, q[9] * c); w1.y = pkh(q[10] * c, q[11] * c); w1.z = pkh(q[12] * c, q[13] * c); w1.w = pkh(q[14] * c, q[15] * c);
;     q0 = __builtin_bit_cast(h16x8, w0); q1 = __builtin_bit_cast(h16x8, w1);
; template <bool ENGINE, int ESTEPS>
; __device__ __forceinline__ void moba_sparse(const Frame& F, const Args& a, int rep) {
;     ...
;                 if (k + 1 < npairs) {
;                     ea = (unsigned)__shfl((int)ment, 32 + (fr < nw1 ? fr : nw1 - 1)); eb = (unsigned)__shfl((int)ment, 32 + (16 + fr < nw1 ? 16 + fr : nw1 - 1));
;                     const f16_t* pa = P + (size_t)(b * SEQ + (int)(ea >> 2)) * NB + h * HD + 8 * G; const f16_t* pb = P + (size_t)(b * SEQ + (int)(eb >> 2)) * NB + h * HD + 8 * G;
;                     ra0 = *(const h16x8*)pa; ra1 = *(const h16x8*)(pa + 32); rb0 = *(const h16x8*)pb; rb1 = *(const h16x8*)(pb + 32); }
.LBB0_1147:
	s_andn2_b64 vcc, exec, s[54:55]
	v_mov_b32_e32 v115, v105
	v_mov_b32_e32 v116, v106
	s_cbranch_vccnz .LBB0_1149
	ds_bpermute_b32 v116, v107, v104
	ds_bpermute_b32 v115, v108, v104
	s_mov_b32 s40, s41
	v_mov_b32_e32 v68, v18
	v_mov_b32_e32 v69, v19
	s_waitcnt lgkmcnt(1)
	v_lshrrev_b32_e32 v2, 2, v116
	s_waitcnt lgkmcnt(0)
	v_lshrrev_b32_e32 v3, 2, v115
	v_add_u32_e32 v2, s25, v2
	v_add_u32_e32 v3, s25, v3
	v_mad_i64_i32 v[6:7], s[8:9], v2, s18, v[66:67]
	v_mad_i64_i32 v[14:15], s[8:9], v3, s18, v[66:67]
	global_load_dwordx4 v[2:5], v[6:7], off
	s_nop 0
	global_load_dwordx4 v[6:9], v[6:7], off offset:64
	s_nop 0
	global_load_dwordx4 v[10:13], v[14:15], off
	s_nop 0
	global_load_dwordx4 v[14:17], v[14:15], off offset:64
	s_mov_b64 s[8:9], s[52:53]
.LBB0_1149:
	v_pk_mul_f32 v[18:19], v[20:21], s[56:57] op_sel_hi:[1,0]
	v_pk_mul_f32 v[20:21], v[22:23], s[56:57] op_sel_hi:[1,0]
	v_cvt_pk_f16_f32 v18, v18, v19
	v_cvt_pk_f16_f32 v19, v20, v21
	v_pk_mul_f32 v[20:21], v[28:29], s[56:57] op_sel_hi:[1,0]
	v_pk_mul_f32 v[22:23], v[32:33], s[56:57] op_sel_hi:[1,0]
	v_cvt_pk_f16_f32 v20, v20, v21
	v_cvt_pk_f16_f32 v21, v22, v23
	v_pk_mul_f32 v[22:23], v[24:25], s[56:57] op_sel_hi:[1,0]
	v_pk_mul_f32 v[24:25], v[36:37], s[56:57] op_sel_hi:[1,0]
	v_cvt_pk_f16_f32 v22, v22, v23
	s_waitcnt lgkmcnt(1)
	v_add_f32_e32 v23, v119, v120
	v_mul_f32_e32 v28, 0x4f800000, v23
	v_cmp_gt_f32_e64 s[54:55], s22, v23
	v_pk_mul_f32 v[26:27], v[26:27], s[56:57] op_sel_hi:[1,0]
	v_pk_mul_f32 v[32:33], v[74:75], s[56:57] op_sel_hi:[1,0]
	v_cndmask_b32_e64 v28, v23, v28, s[54:55]
	v_sqrt_f32_e32 v29, v28
	v_cvt_pk_f16_f32 v23, v24, v25
	v_pk_mul_f32 v[24:25], v[30:31], s[56:57] op_sel_hi:[1,0]
	v_pk_mul_f32 v[34:35], v[34:35], s[56:57] op_sel_hi:[1,0]
	v_cvt_pk_f16_f32 v24, v24, v25
	v_add_u32_e32 v25, -1, v29
	v_fma_f32 v30, -v25, v29, v28
	v_cmp_ge_f32_e32 vcc, 0, v30
	v_add_u32_e32 v30, 1, v29
	v_add_u32_e32 v46, v109, v81
	v_cndmask_b32_e32 v25, v29, v25, vcc
	v_fma_f32 v29, -v30, v29, v28
	v_cmp_lt_f32_e32 vcc, 0, v29
	s_cmp_eq_u32 s69, 0
	s_cselect_b32 s41, s31, s35
	v_cndmask_b32_e32 v25, v25, v30, vcc
	v_mul_f32_e32 v29, 0x37800000, v25
	v_cndmask_b32_e64 v25, v25, v29, s[54:55]
	v_cmp_class_f32_e32 vcc, v28, v101
	v_pk_mul_f32 v[30:31], v[72:73], s[56:57] op_sel_hi:[1,0]
	v_cmp_gt_i32_e64 s[52:53], s41, v1
	v_cndmask_b32_e32 v25, v25, v28, vcc
	v_fma_f32 v36, v92, v25, -4.0
	v_cvt_pk_f16_f32 v25, v26, v27
	v_pk_mul_f32 v[26:27], v[38:39], s[56:57] op_sel_hi:[1,0]
	v_pk_mul_f32 v[28:29], v[40:41], s[56:57] op_sel_hi:[1,0]
	v_cvt_pk_f16_f32 v26, v26, v27
	v_cvt_pk_f16_f32 v27, v28, v29
	v_pk_mul_f32 v[28:29], v[44:45], s[56:57] op_sel_hi:[1,0]
	s_nop 0
	v_cvt_pk_f16_f32 v28, v28, v29
	v_cvt_pk_f16_f32 v29, v30, v31
	v_pk_mul_f32 v[30:31], v[42:43], s[56:57] op_sel_hi:[1,0]
	s_nop 0
	v_cvt_pk_f16_f32 v30, v30, v31
	s_waitcnt lgkmcnt(0)
	v_add_f32_e32 v31, v117, v118
	v_mul_f32_e32 v37, 0x4f800000, v31
	v_cmp_gt_f32_e32 vcc, s22, v31
	s_nop 1
	v_cndmask_b32_e32 v37, v31, v37, vcc
	v_sqrt_f32_e32 v38, v37
	v_cvt_pk_f16_f32 v31, v32, v33
	v_pk_mul_f32 v[32:33], v[70:71], s[56:57] op_sel_hi:[1,0]
	s_nop 0
	v_cvt_pk_f16_f32 v32, v32, v33
	v_add_u32_e32 v33, -1, v38
	v_fma_f32 v39, -v33, v38, v37
	v_cmp_ge_f32_e64 s[54:55], 0, v39
	v_add_u32_e32 v39, 1, v38
	s_nop 0
	v_cndmask_b32_e64 v33, v38, v33, s[54:55]
	v_fma_f32 v38, -v39, v38, v37
	v_cmp_lt_f32_e64 s[54:55], 0, v38
	s_nop 1
	v_cndmask_b32_e64 v33, v33, v39, s[54:55]
	v_mul_f32_e32 v38, 0x37800000, v33
	v_cndmask_b32_e32 v33, v33, v38, vcc
	v_cmp_class_f32_e32 vcc, v37, v101
	v_mul_f32_e32 v38, 0xbfb8aa3b, v36
	v_mov_b32_e32 v39, v38
	v_cndmask_b32_e32 v33, v33, v37, vcc
	v_fma_f32 v42, v92, v33, -4.0
	v_cvt_pk_f16_f32 v33, v34, v35
	ds_read_b128 v[34:37], v110
	ds_read_b128 v[70:73], v110 offset:2048
	ds_read_b128 v[118:121], v111
	ds_read_b128 v[122:125], v111 offset:2048
	ds_read_b64_tr_b16 v[126:127], v46 offset:32768
	ds_read_b64_tr_b16 v[128:129], v46 offset:34816
	ds_read_b64_tr_b16 v[130:131], v112 offset:32768
	ds_read_b64_tr_b16 v[132:133], v112 offset:34816
	ds_read_b64_tr_b16 v[134:135], v113 offset:32768
	ds_read_b64_tr_b16 v[136:137], v113 offset:34816
	ds_read_b64_tr_b16 v[138:139], v114 offset:32768
	ds_read_b64_tr_b16 v[140:141], v114 offset:34816
	v_mul_f32_e32 v42, 0xbfb8aa3b, v42
	v_mov_b32_e32 v40, v38
	v_mov_b32_e32 v41, v38
	v_mov_b32_e32 v43, v42
	v_mov_b32_e32 v44, v42
	v_mov_b32_e32 v45, v42
	s_waitcnt lgkmcnt(11)
	v_mfma_f32_16x16x32_f16 v[142:145], v[34:37], v[18:21], v[38:41]
	v_mfma_f32_16x16x32_f16 v[34:37], v[34:37], v[26:29], v[42:45]
	s_waitcnt lgkmcnt(10)
	v_mfma_f32_16x16x32_f16 v[146:149], v[70:73], v[18:21], v[38:41]
	v_mfma_f32_16x16x32_f16 v[70:73], v[70:73], v[26:29], v[42:45]
	s_waitcnt lgkmcnt(9)
	v_mfma_f32_16x16x32_f16 v[34:37], v[118:121], v[30:33], v[34:37]
	v_mfma_f32_16x16x32_f16 v[142:145], v[118:121], v[22:25], v[142:145]
	s_waitcnt lgkmcnt(8)
; #define LAS __attribute__((address_space(3)))
; template <bool CAUSAL, bool SHARED> ...
;     ...
;     for (int ks = 0; ks < nsteps; ++ks) {
;         LAS const unsigned char* va = Va + ks * 4096 + vrow; LAS const unsigned char* vb = Vb + ks * 4096 + vrow;
;         h16x4 fal[4], fah[4], fbl[4], fbh[4];
; #pragma unroll
;         for (int dt = 0; dt < 4; ++dt) { fal[dt] = vtr(va + ((dt ^ sw) << 5)); fah[dt] = vtr(va + 2048 + ((dt ^ sw) << 5));
;             if (!SHARED) { fbl[dt] = vtr(vb + ((dt ^ sw) << 5)); fbh[dt] = vtr(vb + 2048 + ((dt ^ sw) << 5)); } }
;         __builtin_amdgcn_sched_barrier(0);
;         f32x4 sa0, sa1, sb0, sb1;
;         sa0 = __builtin_amdgcn_mfma_f32_16x16x32_f16(ka[0], qa0, nma, 0, 0, 0); sb0 = __builtin_amdgcn_mfma_f32_16x16x32_f16(SHARED ? ka[0] : kb[0], qb0, nmb, 0, 0, 0);
;         sa1 = __builtin_amdgcn_mfma_f32_16x16x32_f16(ka[2], qa0, nma, 0, 0, 0); sb1 = __builtin_amdgcn_mfma_f32_16x16x32_f16(SHARED ? ka[2] : kb[2], qb0, nmb, 0, 0, 0);
;         sa0 = __builtin_amdgcn_mfma_f32_16x16x32_f16(ka[1], qa1, sa0, 0, 0, 0); sb0 = __builtin_amdgcn_mfma_f32_16x16x32_f16(SHARED ? ka[1] : kb[1], qb1, sb0, 0, 0, 0);
;         sa1 = __builtin_amdgcn_mfma_f32_16x16x32_f16(ka[3], qa1, sa1, 0, 0, 0); sb1 = __builtin_amdgcn_mfma_f32_16x16x32_f16(SHARED ? ka[3] : kb[3], qb1, sb1, 0, 0, 0);
;         __builtin_amdgcn_sched_barrier(0);
;         if (ks + 1 < nsteps) { LAS const unsigned char* kn = Ka + (ks + 1) * 4096;
;             ka[0] = *(LAS const h16x8*)(kn + kof0); ka[1] = *(LAS const h16x8*)(kn + kof1); ka[2] = *(LAS const h16x8*)(kn + 2048 + kof0); ka[3] = *(LAS const h16x8*)(kn + 2048 + kof1);
;             if (!SHARED) { LAS const unsigned char* kn2 = Kb + (ks + 1) * 4096;
;                 kb[0] = *(LAS const h16x8*)(kn2 + kof0); kb[1] = *(LAS const h16x8*)(kn2 + kof1); kb[2] = *(LAS const h16x8*)(kn2 + 2048 + kof0); kb[3] = *(LAS const h16x8*)(kn2 + 2048 + kof1); } }
;         __builtin_amdgcn_sched_barrier(0);
;         f32x4 pa0, pa1, pb0, pb1;
; #pragma unroll
;         for (int e = 0; e < 4; ++e) { pa0[e] = __builtin_amdgcn_exp2f(sa0[e]); pa1[e] = __builtin_amdgcn_exp2f(sa1[e]);
;                                       pb0[e] = __builtin_amdgcn_exp2f(sb0[e]); pb1[e] = __builtin_amdgcn_exp2f(sb1[e]); }
;         if (CAUSAL) { const int kr = ks * 32 + 4 * G;
; #pragma unroll
	v_mfma_f32_16x16x32_f16 v[118:121], v[122:125], v[22:25], v[146:149]
	v_mfma_f32_16x16x32_f16 v[70:73], v[122:125], v[30:33], v[70:73]
	ds_read_b128 v[122:125], v111 offset:6144
	s_nop 0
	ds_read_b128 v[146:149], v111 offset:4096
	ds_read_b128 v[150:153], v110 offset:6144
	ds_read_b128 v[154:157], v110 offset:4096
	ds_read_b64_tr_b16 v[170:171], v46 offset:36864
	ds_read_b64_tr_b16 v[172:173], v46 offset:38912
	ds_read_b64_tr_b16 v[174:175], v112 offset:36864
	ds_read_b64_tr_b16 v[176:177], v112 offset:38912
	ds_read_b64_tr_b16 v[178:179], v113 offset:36864
	ds_read_b64_tr_b16 v[180:181], v113 offset:38912
	ds_read_b64_tr_b16 v[182:183], v114 offset:36864
	ds_read_b64_tr_b16 v[184:185], v114 offset:38912
	v_exp_f32_e32 v74, v142
	v_exp_f32_e32 v75, v118
	v_exp_f32_e32 v34, v34
	v_exp_f32_e32 v117, v70
	v_exp_f32_e32 v70, v143
	v_exp_f32_e32 v118, v119
	v_exp_f32_e32 v35, v35
	v_exp_f32_e32 v142, v71
	v_exp_f32_e32 v71, v144
	v_exp_f32_e32 v119, v120
	v_exp_f32_e32 v36, v36
	v_exp_f32_e32 v143, v72
	v_exp_f32_e32 v72, v145
	v_exp_f32_e32 v120, v121
	v_exp_f32_e32 v37, v37
	s_mov_b32 s69, s68
	v_exp_f32_e32 v121, v73
	v_cvt_pk_f16_f32 v71, v71, v72
	v_cvt_pk_f16_f32 v72, v75, v118
	v_cvt_pk_f16_f32 v73, v119, v120
	v_cvt_pk_f16_f32 v118, v34, v35
	v_cvt_pk_f16_f32 v119, v36, v37
	s_mov_b32 s70, s68
	s_mov_b32 s71, s68
	v_mov_b64_e32 v[34:35], s[68:69]
	v_mov_b64_e32 v[36:37], s[70:71]
	v_cvt_pk_f16_f32 v70, v74, v70
	v_cvt_pk_f16_f32 v120, v117, v142
	v_cvt_pk_f16_f32 v121, v143, v121
	v_mfma_f32_16x16x32_f16 v[142:145], v[34:37], v[70:73], 0
	s_waitcnt lgkmcnt(14)
	v_mfma_f32_16x16x32_f16 v[158:161], v[126:129], v[70:73], 0
	v_mfma_f32_16x16x32_f16 v[126:129], v[126:129], v[118:121], 0
	v_mfma_f32_16x16x32_f16 v[162:165], v[130:133], v[70:73], 0
	v_mfma_f32_16x16x32_f16 v[130:133], v[130:133], v[118:121], 0
	v_mfma_f32_16x16x32_f16 v[166:169], v[134:137], v[70:73], 0
	v_mfma_f32_16x16x32_f16 v[134:137], v[134:137], v[118:121], 0
	s_waitcnt lgkmcnt(12)
	v_mfma_f32_16x16x32_f16 v[70:73], v[138:141], v[70:73], 0
	v_mfma_f32_16x16x32_f16 v[138:141], v[138:141], v[118:121], 0
	v_mfma_f32_16x16x32_f16 v[118:121], v[34:37], v[118:121], 0
	s_waitcnt lgkmcnt(8)
	v_mfma_f32_16x16x32_f16 v[186:189], v[154:157], v[18:21], v[38:41]
	v_mfma_f32_16x16x32_f16 v[154:157], v[154:157], v[26:29], v[42:45]
	v_mfma_f32_16x16x32_f16 v[190:193], v[150:153], v[18:21], v[38:41]
	v_mfma_f32_16x16x32_f16 v[150:153], v[150:153], v[26:29], v[42:45]
	v_mfma_f32_16x16x32_f16 v[186:189], v[146:149], v[22:25], v[186:189]
	v_mfma_f32_16x16x32_f16 v[146:149], v[146:149], v[30:33], v[154:157]
	v_mfma_f32_16x16x32_f16 v[154:157], v[122:125], v[22:25], v[190:193]
	v_mfma_f32_16x16x32_f16 v[122:125], v[122:125], v[30:33], v[150:153]
	s_nop 3
	ds_read_b128 v[150:153], v111 offset:10240
	ds_read_b128 v[190:193], v111 offset:8192
	ds_read_b128 v[194:197], v110 offset:10240
	ds_read_b128 v[198:201], v110 offset:8192
	v_exp_f32_e32 v74, v186
	v_exp_f32_e32 v75, v154
	v_exp_f32_e32 v117, v146
	v_exp_f32_e32 v186, v122
	v_exp_f32_e32 v122, v187
	v_exp_f32_e32 v146, v155
	v_exp_f32_e32 v147, v147
	v_exp_f32_e32 v187, v123
	v_exp_f32_e32 v123, v188
	v_exp_f32_e32 v188, v156
	v_exp_f32_e32 v202, v148
	v_exp_f32_e32 v148, v189
	v_exp_f32_e32 v189, v124
	v_exp_f32_e32 v124, v157
	v_cvt_pk_f16_f32 v154, v74, v122
	v_cvt_pk_f16_f32 v156, v75, v146
	v_exp_f32_e32 v74, v149
	v_exp_f32_e32 v75, v125
	v_cvt_pk_f16_f32 v155, v123, v148
	v_cvt_pk_f16_f32 v157, v188, v124
	v_cvt_pk_f16_f32 v122, v117, v147
	v_cvt_pk_f16_f32 v123, v202, v74
	v_cvt_pk_f16_f32 v124, v186, v187
	v_cvt_pk_f16_f32 v125, v189, v75
	v_mfma_f32_16x16x32_f16 v[142:145], v[34:37], v[154:157], v[142:145]
	s_waitcnt lgkmcnt(10)
	v_mfma_f32_16x16x32_f16 v[146:149], v[170:173], v[154:157], v[158:161]
	v_mfma_f32_16x16x32_f16 v[126:129], v[170:173], v[122:125], v[126:129]
	s_waitcnt lgkmcnt(8)
	v_mfma_f32_16x16x32_f16 v[158:161], v[174:177], v[154:157], v[162:165]
	v_mfma_f32_16x16x32_f16 v[130:133], v[174:177], v[122:125], v[130:133]
	s_waitcnt lgkmcnt(6)
	v_mfma_f32_16x16x32_f16 v[162:165], v[178:181], v[154:157], v[166:169]
	s_waitcnt lgkmcnt(4)
	v_mfma_f32_16x16x32_f16 v[70:73], v[182:185], v[154:157], v[70:73]
	ds_read_b64_tr_b16 v[154:155], v46 offset:40960
	ds_read_b64_tr_b16 v[156:157], v46 offset:43008
	ds_read_b64_tr_b16 v[166:167], v112 offset:40960
	ds_read_b64_tr_b16 v[168:169], v112 offset:43008
	ds_read_b64_tr_b16 v[170:171], v113 offset:40960
	ds_read_b64_tr_b16 v[172:173], v113 offset:43008
	ds_read_b64_tr_b16 v[174:175], v114 offset:40960
	ds_read_b64_tr_b16 v[176:177], v114 offset:43008
	v_mfma_f32_16x16x32_f16 v[134:137], v[178:181], v[122:125], v[134:137]
	v_mfma_f32_16x16x32_f16 v[138:141], v[182:185], v[122:125], v[138:141]
	v_mfma_f32_16x16x32_f16 v[118:121], v[34:37], v[122:125], v[118:121]
	s_waitcnt lgkmcnt(8)
	v_mfma_f32_16x16x32_f16 v[122:125], v[198:201], v[18:21], v[38:41]
	v_mfma_f32_16x16x32_f16 v[178:181], v[198:201], v[26:29], v[42:45]
	v_mfma_f32_16x16x32_f16 v[182:185], v[194:197], v[18:21], v[38:41]
	v_mfma_f32_16x16x32_f16 v[186:189], v[194:197], v[26:29], v[42:45]
	v_mfma_f32_16x16x32_f16 v[122:125], v[190:193], v[22:25], v[122:125]
	v_mfma_f32_16x16x32_f16 v[178:181], v[190:193], v[30:33], v[178:181]
	v_mfma_f32_16x16x32_f16 v[182:185], v[150:153], v[22:25], v[182:185]
	v_mfma_f32_16x16x32_f16 v[150:153], v[150:153], v[30:33], v[186:189]
	s_nop 3
	ds_read_b128 v[186:189], v111 offset:14336
	ds_read_b128 v[190:193], v111 offset:12288
	ds_read_b128 v[194:197], v110 offset:14336
	ds_read_b128 v[198:201], v110 offset:12288
	v_exp_f32_e32 v74, v122
	v_exp_f32_e32 v75, v182
	v_exp_f32_e32 v117, v178
	v_exp_f32_e32 v178, v150
	v_exp_f32_e32 v122, v123
	v_exp_f32_e32 v150, v183
	v_exp_f32_e32 v123, v124
	v_exp_f32_e32 v124, v125
	v_exp_f32_e32 v179, v179
	v_exp_f32_e32 v182, v151
	v_exp_f32_e32 v151, v184
	v_exp_f32_e32 v180, v180
	v_exp_f32_e32 v183, v152
	v_exp_f32_e32 v125, v185
	v_cvt_pk_f16_f32 v122, v74, v122
	v_cvt_pk_f16_f32 v123, v123, v124
	v_cvt_pk_f16_f32 v124, v75, v150
	v_exp_f32_e32 v74, v181
	v_exp_f32_e32 v75, v153
	v_cvt_pk_f16_f32 v125, v151, v125
	v_cvt_pk_f16_f32 v150, v117, v179
	v_cvt_pk_f16_f32 v151, v180, v74
	v_cvt_pk_f16_f32 v152, v178, v182
	v_cvt_pk_f16_f32 v153, v183, v75
	v_mfma_f32_16x16x32_f16 v[142:145], v[34:37], v[122:125], v[142:145]
	s_waitcnt lgkmcnt(10)
; #define LAS __attribute__((address_space(3)))
; template <bool CAUSAL, bool SHARED> ...
;     ...
;     for (int ks = 0; ks < nsteps; ++ks) {
;         LAS const unsigned char* va = Va + ks * 4096 + vrow; LAS const unsigned char* vb = Vb + ks * 4096 + vrow;
;         h16x4 fal[4], fah[4], fbl[4], fbh[4];
; #pragma unroll
;         for (int dt = 0; dt < 4; ++dt) { fal[dt] = vtr(va + ((dt ^ sw) << 5)); fah[dt] = vtr(va + 2048 + ((dt ^ sw) << 5));
;             if (!SHARED) { fbl[dt] = vtr(vb + ((dt ^ sw) << 5)); fbh[dt] = vtr(vb + 2048 + ((dt ^ sw) << 5)); } }
;         __builtin_amdgcn_sched_barrier(0);
;         f32x4 sa0, sa1, sb0, sb1;
;         sa0 = __builtin_amdgcn_mfma_f32_16x16x32_f16(ka[0], qa0, nma, 0, 0, 0); sb0 = __builtin_amdgcn_mfma_f32_16x16x32_f16(SHARED ? ka[0] : kb[0], qb0, nmb, 0, 0, 0);
;         sa1 = __builtin_amdgcn_mfma_f32_16x16x32_f16(ka[2], qa0, nma, 0, 0, 0); sb1 = __builtin_amdgcn_mfma_f32_16x16x32_f16(SHARED ? ka[2] : kb[2], qb0, nmb, 0, 0, 0);
;         sa0 = __builtin_amdgcn_mfma_f32_16x16x32_f16(ka[1], qa1, sa0, 0, 0, 0); sb0 = __builtin_amdgcn_mfma_f32_16x16x32_f16(SHARED ? ka[1] : kb[1], qb1, sb0, 0, 0, 0);
;         sa1 = __builtin_amdgcn_mfma_f32_16x16x32_f16(ka[3], qa1, sa1, 0, 0, 0); sb1 = __builtin_amdgcn_mfma_f32_16x16x32_f16(SHARED ? ka[3] : kb[3], qb1, sb1, 0, 0, 0);
;         __builtin_amdgcn_sched_barrier(0);
;         if (ks + 1 < nsteps) { LAS const unsigned char* kn = Ka + (ks + 1) * 4096;
;             ka[0] = *(LAS const h16x8*)(kn + kof0); ka[1] = *(LAS const h16x8*)(kn + kof1); ka[2] = *(LAS const h16x8*)(kn + 2048 + kof0); ka[3] = *(LAS const h16x8*)(kn + 2048 + kof1);
;             if (!SHARED) { LAS const unsigned char* kn2 = Kb + (ks + 1) * 4096;
;                 kb[0] = *(LAS const h16x8*)(kn2 + kof0); kb[1] = *(LAS const h16x8*)(kn2 + kof1); kb[2] = *(LAS const h16x8*)(kn2 + 2048 + kof0); kb[3] = *(LAS const h16x8*)(kn2 + 2048 + kof1); } }
;         __builtin_amdgcn_sched_barrier(0);
;         f32x4 pa0, pa1, pb0, pb1;
; #pragma unroll
;         for (int e = 0; e < 4; ++e) { pa0[e] = __builtin_amdgcn_exp2f(sa0[e]); pa1[e] = __builtin_amdgcn_exp2f(sa1[e]);
;                                       pb0[e] = __builtin_amdgcn_exp2f(sb0[e]); pb1[e] = __builtin_amdgcn_exp2f(sb1[e]); }
;         if (CAUSAL) { const int kr = ks * 32 + 4 * G;
; #pragma unroll
	v_mfma_f32_16x16x32_f16 v[146:149], v[154:157], v[122:125], v[146:149]
	v_mfma_f32_16x16x32_f16 v[126:129], v[154:157], v[150:153], v[126:129]
	s_waitcnt lgkmcnt(8)
	v_mfma_f32_16x16x32_f16 v[154:157], v[166:169], v[122:125], v[158:161]
	v_mfma_f32_16x16x32_f16 v[130:133], v[166:169], v[150:153], v[130:133]
	s_waitcnt lgkmcnt(6)
	v_mfma_f32_16x16x32_f16 v[158:161], v[170:173], v[122:125], v[162:165]
	v_mfma_f32_16x16x32_f16 v[134:137], v[170:173], v[150:153], v[134:137]
	s_waitcnt lgkmcnt(4)
	v_mfma_f32_16x16x32_f16 v[70:73], v[174:177], v[122:125], v[70:73]
	v_mfma_f32_16x16x32_f16 v[122:125], v[174:177], v[150:153], v[138:141]
	s_nop 2
	ds_read_b64_tr_b16 v[138:139], v46 offset:45056
	ds_read_b64_tr_b16 v[140:141], v46 offset:47104
	ds_read_b64_tr_b16 v[162:163], v112 offset:45056
	ds_read_b64_tr_b16 v[164:165], v112 offset:47104
	ds_read_b64_tr_b16 v[166:167], v113 offset:45056
	ds_read_b64_tr_b16 v[168:169], v113 offset:47104
	ds_read_b64_tr_b16 v[170:171], v114 offset:45056
	ds_read_b64_tr_b16 v[172:173], v114 offset:47104
	v_mfma_f32_16x16x32_f16 v[118:121], v[34:37], v[150:153], v[118:121]
	s_waitcnt lgkmcnt(8)
	v_mfma_f32_16x16x32_f16 v[150:153], v[198:201], v[18:21], v[38:41]
	v_mfma_f32_16x16x32_f16 v[174:177], v[198:201], v[26:29], v[42:45]
	v_mfma_f32_16x16x32_f16 v[178:181], v[194:197], v[18:21], v[38:41]
	v_mfma_f32_16x16x32_f16 v[182:185], v[194:197], v[26:29], v[42:45]
	v_mfma_f32_16x16x32_f16 v[150:153], v[190:193], v[22:25], v[150:153]
	v_mfma_f32_16x16x32_f16 v[174:177], v[190:193], v[30:33], v[174:177]
	v_mfma_f32_16x16x32_f16 v[178:181], v[186:189], v[22:25], v[178:181]
	v_mfma_f32_16x16x32_f16 v[182:185], v[186:189], v[30:33], v[182:185]
	ds_read_b128 v[186:189], v111 offset:18432
	ds_read_b128 v[190:193], v111 offset:16384
	ds_read_b128 v[194:197], v110 offset:18432
	ds_read_b128 v[198:201], v110 offset:16384
	s_nop 0
	v_exp_f32_e32 v74, v150
	s_nop 0
	v_exp_f32_e32 v75, v178
	v_exp_f32_e32 v117, v174
	v_exp_f32_e32 v150, v151
	v_exp_f32_e32 v174, v179
	v_exp_f32_e32 v151, v152
	v_exp_f32_e32 v152, v153
	v_exp_f32_e32 v178, v182
	v_exp_f32_e32 v175, v175
	v_exp_f32_e32 v179, v183
	v_exp_f32_e32 v180, v180
	v_exp_f32_e32 v176, v176
	v_exp_f32_e32 v182, v184
	v_exp_f32_e32 v153, v181
	v_cvt_pk_f16_f32 v150, v74, v150
	v_cvt_pk_f16_f32 v151, v151, v152
	v_cvt_pk_f16_f32 v152, v75, v174
	v_exp_f32_e32 v74, v177
	v_exp_f32_e32 v75, v185
	v_cvt_pk_f16_f32 v153, v180, v153
	v_cvt_pk_f16_f32 v174, v117, v175
	v_cvt_pk_f16_f32 v175, v176, v74
	v_cvt_pk_f16_f32 v176, v178, v179
	v_cvt_pk_f16_f32 v177, v182, v75
	v_mfma_f32_16x16x32_f16 v[142:145], v[34:37], v[150:153], v[142:145]
	s_waitcnt lgkmcnt(10)
	v_mfma_f32_16x16x32_f16 v[146:149], v[138:141], v[150:153], v[146:149]
	v_mfma_f32_16x16x32_f16 v[126:129], v[138:141], v[174:177], v[126:129]
	s_waitcnt lgkmcnt(8)
	v_mfma_f32_16x16x32_f16 v[138:141], v[162:165], v[150:153], v[154:157]
	v_mfma_f32_16x16x32_f16 v[130:133], v[162:165], v[174:177], v[130:133]
	s_waitcnt lgkmcnt(6)
	v_mfma_f32_16x16x32_f16 v[154:157], v[166:169], v[150:153], v[158:161]
	v_mfma_f32_16x16x32_f16 v[134:137], v[166:169], v[174:177], v[134:137]
	s_waitcnt lgkmcnt(4)
	v_mfma_f32_16x16x32_f16 v[70:73], v[170:173], v[150:153], v[70:73]
	ds_read_b64_tr_b16 v[150:151], v46 offset:49152
	ds_read_b64_tr_b16 v[152:153], v46 offset:51200
	ds_read_b64_tr_b16 v[158:159], v112 offset:49152
	ds_read_b64_tr_b16 v[160:161], v112 offset:51200
	ds_read_b64_tr_b16 v[162:163], v113 offset:49152
	ds_read_b64_tr_b16 v[164:165], v113 offset:51200
	ds_read_b64_tr_b16 v[166:167], v114 offset:49152
	ds_read_b64_tr_b16 v[168:169], v114 offset:51200
	v_mfma_f32_16x16x32_f16 v[122:125], v[170:173], v[174:177], v[122:125]
	v_mfma_f32_16x16x32_f16 v[118:121], v[34:37], v[174:177], v[118:121]
	s_waitcnt lgkmcnt(8)
	v_mfma_f32_16x16x32_f16 v[170:173], v[198:201], v[18:21], v[38:41]
	v_mfma_f32_16x16x32_f16 v[174:177], v[198:201], v[26:29], v[42:45]
	v_mfma_f32_16x16x32_f16 v[178:181], v[194:197], v[18:21], v[38:41]
	v_mfma_f32_16x16x32_f16 v[182:185], v[194:197], v[26:29], v[42:45]
	v_mfma_f32_16x16x32_f16 v[170:173], v[190:193], v[22:25], v[170:173]
	v_mfma_f32_16x16x32_f16 v[174:177], v[190:193], v[30:33], v[174:177]
	v_mfma_f32_16x16x32_f16 v[178:181], v[186:189], v[22:25], v[178:181]
	v_mfma_f32_16x16x32_f16 v[182:185], v[186:189], v[30:33], v[182:185]
	ds_read_b128 v[186:189], v111 offset:22528
	ds_read_b128 v[190:193], v111 offset:20480
	ds_read_b128 v[194:197], v110 offset:22528
	ds_read_b128 v[198:201], v110 offset:20480
	s_nop 0
	v_exp_f32_e32 v74, v170
	s_nop 0
	v_exp_f32_e32 v75, v178
	v_exp_f32_e32 v117, v174
	v_exp_f32_e32 v170, v171
	v_exp_f32_e32 v174, v179
	v_exp_f32_e32 v171, v172
	v_exp_f32_e32 v172, v173
	v_exp_f32_e32 v178, v182
	v_exp_f32_e32 v175, v175
	v_exp_f32_e32 v179, v183
	v_exp_f32_e32 v180, v180
	v_exp_f32_e32 v176, v176
	v_exp_f32_e32 v182, v184
	v_exp_f32_e32 v173, v181
	v_cvt_pk_f16_f32 v170, v74, v170
	v_cvt_pk_f16_f32 v171, v171, v172
	v_cvt_pk_f16_f32 v172, v75, v174
	v_exp_f32_e32 v74, v177
	v_exp_f32_e32 v75, v185
	v_cvt_pk_f16_f32 v173, v180, v173
	v_cvt_pk_f16_f32 v174, v117, v175
	v_cvt_pk_f16_f32 v175, v176, v74
	v_cvt_pk_f16_f32 v176, v178, v179
	v_cvt_pk_f16_f32 v177, v182, v75
	s_waitcnt lgkmcnt(10)
	v_mfma_f32_16x16x32_f16 v[146:149], v[150:153], v[170:173], v[146:149]
	v_mfma_f32_16x16x32_f16 v[126:129], v[150:153], v[174:177], v[126:129]
	s_waitcnt lgkmcnt(8)
	v_mfma_f32_16x16x32_f16 v[138:141], v[158:161], v[170:173], v[138:141]
	v_mfma_f32_16x16x32_f16 v[130:133], v[158:161], v[174:177], v[130:133]
	s_waitcnt lgkmcnt(6)
; #define LAS __attribute__((address_space(3)))
; template <bool CAUSAL, bool SHARED> ...
;     ...
;     for (int ks = 0; ks < nsteps; ++ks) {
;         LAS const unsigned char* va = Va + ks * 4096 + vrow; LAS const unsigned char* vb = Vb + ks * 4096 + vrow;
;         h16x4 fal[4], fah[4], fbl[4], fbh[4];
; #pragma unroll
;         for (int dt = 0; dt < 4; ++dt) { fal[dt] = vtr(va + ((dt ^ sw) << 5)); fah[dt] = vtr(va + 2048 + ((dt ^ sw) << 5));
;             if (!SHARED) { fbl[dt] = vtr(vb + ((dt ^ sw) << 5)); fbh[dt] = vtr(vb + 2048 + ((dt ^ sw) << 5)); } }
;         __builtin_amdgcn_sched_barrier(0);
;         f32x4 sa0, sa1, sb0, sb1;
;         sa0 = __builtin_amdgcn_mfma_f32_16x16x32_f16(ka[0], qa0, nma, 0, 0, 0); sb0 = __builtin_amdgcn_mfma_f32_16x16x32_f16(SHARED ? ka[0] : kb[0], qb0, nmb, 0, 0, 0);
;         sa1 = __builtin_amdgcn_mfma_f32_16x16x32_f16(ka[2], qa0, nma, 0, 0, 0); sb1 = __builtin_amdgcn_mfma_f32_16x16x32_f16(SHARED ? ka[2] : kb[2], qb0, nmb, 0, 0, 0);
;         sa0 = __builtin_amdgcn_mfma_f32_16x16x32_f16(ka[1], qa1, sa0, 0, 0, 0); sb0 = __builtin_amdgcn_mfma_f32_16x16x32_f16(SHARED ? ka[1] : kb[1], qb1, sb0, 0, 0, 0);
;         sa1 = __builtin_amdgcn_mfma_f32_16x16x32_f16(ka[3], qa1, sa1, 0, 0, 0); sb1 = __builtin_amdgcn_mfma_f32_16x16x32_f16(SHARED ? ka[3] : kb[3], qb1, sb1, 0, 0, 0);
;         __builtin_amdgcn_sched_barrier(0);
;         if (ks + 1 < nsteps) { LAS const unsigned char* kn = Ka + (ks + 1) * 4096;
;             ka[0] = *(LAS const h16x8*)(kn + kof0); ka[1] = *(LAS const h16x8*)(kn + kof1); ka[2] = *(LAS const h16x8*)(kn + 2048 + kof0); ka[3] = *(LAS const h16x8*)(kn + 2048 + kof1);
;             if (!SHARED) { LAS const unsigned char* kn2 = Kb + (ks + 1) * 4096;
;                 kb[0] = *(LAS const h16x8*)(kn2 + kof0); kb[1] = *(LAS const h16x8*)(kn2 + kof1); kb[2] = *(LAS const h16x8*)(kn2 + 2048 + kof0); kb[3] = *(LAS const h16x8*)(kn2 + 2048 + kof1); } }
;         __builtin_amdgcn_sched_barrier(0);
;         f32x4 pa0, pa1, pb0, pb1;
; #pragma unroll
;         for (int e = 0; e < 4; ++e) { pa0[e] = __builtin_amdgcn_exp2f(sa0[e]); pa1[e] = __builtin_amdgcn_exp2f(sa1[e]);
;                                       pb0[e] = __builtin_amdgcn_exp2f(sb0[e]); pb1[e] = __builtin_amdgcn_exp2f(sb1[e]); }
;         if (CAUSAL) { const int kr = ks * 32 + 4 * G;
; #pragma unroll
	v_mfma_f32_16x16x32_f16 v[150:153], v[162:165], v[170:173], v[154:157]
	v_mfma_f32_16x16x32_f16 v[134:137], v[162:165], v[174:177], v[134:137]
	s_waitcnt lgkmcnt(4)
	v_mfma_f32_16x16x32_f16 v[70:73], v[166:169], v[170:173], v[70:73]
	v_mfma_f32_16x16x32_f16 v[122:125], v[166:169], v[174:177], v[122:125]
	ds_read_b64_tr_b16 v[154:155], v46 offset:53248
	ds_read_b64_tr_b16 v[156:157], v46 offset:55296
	ds_read_b64_tr_b16 v[158:159], v112 offset:53248
	ds_read_b64_tr_b16 v[160:161], v112 offset:55296
	ds_read_b64_tr_b16 v[162:163], v113 offset:53248
	ds_read_b64_tr_b16 v[164:165], v113 offset:55296
	ds_read_b64_tr_b16 v[166:167], v114 offset:53248
	ds_read_b64_tr_b16 v[168:169], v114 offset:55296
	v_mfma_f32_16x16x32_f16 v[142:145], v[34:37], v[170:173], v[142:145]
	v_mfma_f32_16x16x32_f16 v[118:121], v[34:37], v[174:177], v[118:121]
	s_waitcnt lgkmcnt(8)
	v_mfma_f32_16x16x32_f16 v[170:173], v[198:201], v[18:21], v[38:41]
	v_mfma_f32_16x16x32_f16 v[174:177], v[198:201], v[26:29], v[42:45]
	v_mfma_f32_16x16x32_f16 v[178:181], v[194:197], v[18:21], v[38:41]
	v_mfma_f32_16x16x32_f16 v[182:185], v[194:197], v[26:29], v[42:45]
	v_mfma_f32_16x16x32_f16 v[170:173], v[190:193], v[22:25], v[170:173]
	v_mfma_f32_16x16x32_f16 v[174:177], v[190:193], v[30:33], v[174:177]
	v_mfma_f32_16x16x32_f16 v[178:181], v[186:189], v[22:25], v[178:181]
	v_mfma_f32_16x16x32_f16 v[182:185], v[186:189], v[30:33], v[182:185]
	ds_read_b128 v[186:189], v111 offset:26624
	ds_read_b128 v[190:193], v111 offset:24576
	ds_read_b128 v[194:197], v110 offset:26624
	ds_read_b128 v[198:201], v110 offset:24576
	s_nop 0
	v_exp_f32_e32 v74, v170
	s_nop 0
	v_exp_f32_e32 v75, v178
	v_exp_f32_e32 v117, v174
	v_exp_f32_e32 v170, v171
	v_exp_f32_e32 v174, v179
	v_exp_f32_e32 v171, v172
	v_exp_f32_e32 v172, v173
	v_exp_f32_e32 v178, v182
	v_exp_f32_e32 v175, v175
	v_exp_f32_e32 v179, v183
	v_exp_f32_e32 v180, v180
	v_exp_f32_e32 v176, v176
	v_exp_f32_e32 v182, v184
	v_exp_f32_e32 v173, v181
	v_cvt_pk_f16_f32 v170, v74, v170
	v_cvt_pk_f16_f32 v171, v171, v172
	v_cvt_pk_f16_f32 v172, v75, v174
	v_exp_f32_e32 v74, v177
	v_exp_f32_e32 v75, v185
	v_cvt_pk_f16_f32 v173, v180, v173
	v_cvt_pk_f16_f32 v174, v117, v175
	v_cvt_pk_f16_f32 v175, v176, v74
	v_cvt_pk_f16_f32 v176, v178, v179
	v_cvt_pk_f16_f32 v177, v182, v75
	s_waitcnt lgkmcnt(10)
	v_mfma_f32_16x16x32_f16 v[146:149], v[154:157], v[170:173], v[146:149]
	v_mfma_f32_16x16x32_f16 v[126:129], v[154:157], v[174:177], v[126:129]
	s_waitcnt lgkmcnt(8)
	v_mfma_f32_16x16x32_f16 v[138:141], v[158:161], v[170:173], v[138:141]
	v_mfma_f32_16x16x32_f16 v[130:133], v[158:161], v[174:177], v[130:133]
	s_waitcnt lgkmcnt(6)
	v_mfma_f32_16x16x32_f16 v[150:153], v[162:165], v[170:173], v[150:153]
	v_mfma_f32_16x16x32_f16 v[134:137], v[162:165], v[174:177], v[134:137]
	s_waitcnt lgkmcnt(4)
	v_mfma_f32_16x16x32_f16 v[70:73], v[166:169], v[170:173], v[70:73]
	v_mfma_f32_16x16x32_f16 v[122:125], v[166:169], v[174:177], v[122:125]
	ds_read_b64_tr_b16 v[154:155], v46 offset:57344
	ds_read_b64_tr_b16 v[156:157], v46 offset:59392
	ds_read_b64_tr_b16 v[158:159], v112 offset:57344
	ds_read_b64_tr_b16 v[160:161], v112 offset:59392
	ds_read_b64_tr_b16 v[162:163], v113 offset:57344
	ds_read_b64_tr_b16 v[164:165], v113 offset:59392
	ds_read_b64_tr_b16 v[166:167], v114 offset:57344
	ds_read_b64_tr_b16 v[168:169], v114 offset:59392
	v_mfma_f32_16x16x32_f16 v[142:145], v[34:37], v[170:173], v[142:145]
	v_mfma_f32_16x16x32_f16 v[118:121], v[34:37], v[174:177], v[118:121]
	s_waitcnt lgkmcnt(8)
	v_mfma_f32_16x16x32_f16 v[170:173], v[198:201], v[18:21], v[38:41]
	v_mfma_f32_16x16x32_f16 v[174:177], v[198:201], v[26:29], v[42:45]
	v_mfma_f32_16x16x32_f16 v[178:181], v[194:197], v[18:21], v[38:41]
	v_mfma_f32_16x16x32_f16 v[182:185], v[194:197], v[26:29], v[42:45]
	v_mfma_f32_16x16x32_f16 v[170:173], v[190:193], v[22:25], v[170:173]
	v_mfma_f32_16x16x32_f16 v[174:177], v[190:193], v[30:33], v[174:177]
	v_mfma_f32_16x16x32_f16 v[178:181], v[186:189], v[22:25], v[178:181]
	v_mfma_f32_16x16x32_f16 v[182:185], v[186:189], v[30:33], v[182:185]
	ds_read_b128 v[186:189], v111 offset:30720
	ds_read_b128 v[190:193], v111 offset:28672
	ds_read_b128 v[194:197], v110 offset:30720
	ds_read_b128 v[198:201], v110 offset:28672
	s_nop 0
	v_exp_f32_e32 v74, v170
	s_nop 0
	v_exp_f32_e32 v75, v178
	v_exp_f32_e32 v117, v174
	v_exp_f32_e32 v170, v171
	v_exp_f32_e32 v174, v179
	v_exp_f32_e32 v171, v172
	v_exp_f32_e32 v172, v173
	v_exp_f32_e32 v178, v182
	v_exp_f32_e32 v175, v175
	v_exp_f32_e32 v179, v183
	v_exp_f32_e32 v180, v180
	v_exp_f32_e32 v176, v176
	v_exp_f32_e32 v182, v184
	v_exp_f32_e32 v173, v181
	v_cvt_pk_f16_f32 v170, v74, v170
	v_cvt_pk_f16_f32 v171, v171, v172
	v_cvt_pk_f16_f32 v172, v75, v174
	v_exp_f32_e32 v74, v177
	v_exp_f32_e32 v75, v185
	v_cvt_pk_f16_f32 v173, v180, v173
	v_cvt_pk_f16_f32 v174, v117, v175
	v_cvt_pk_f16_f32 v175, v176, v74
	v_cvt_pk_f16_f32 v176, v178, v179
	v_cvt_pk_f16_f32 v177, v182, v75
	s_waitcnt lgkmcnt(10)
	v_mfma_f32_16x16x32_f16 v[146:149], v[154:157], v[170:173], v[146:149]
	v_mfma_f32_16x16x32_f16 v[126:129], v[154:157], v[174:177], v[126:129]
	s_waitcnt lgkmcnt(8)
	v_mfma_f32_16x16x32_f16 v[138:141], v[158:161], v[170:173], v[138:141]
	v_mfma_f32_16x16x32_f16 v[130:133], v[158:161], v[174:177], v[130:133]
	s_waitcnt lgkmcnt(6)
	v_mfma_f32_16x16x32_f16 v[150:153], v[162:165], v[170:173], v[150:153]
	v_mfma_f32_16x16x32_f16 v[134:137], v[162:165], v[174:177], v[134:137]
	s_waitcnt lgkmcnt(4)
; __device__ __forceinline__ unsigned pkh(float lo, float hi) { f32x2 v = {lo, hi}; h16x2 h = __builtin_convertvector(v, h16x2); return __builtin_bit_cast(unsigned, h); }
; __device__ __forceinline__ h16x8 cat8(h16x4 lo, h16x4 hi) { return (h16x8){lo[0], lo[1], lo[2], lo[3], hi[0], hi[1], hi[2], hi[3]}; }
; template <bool CAUSAL, bool SHARED> ...
;     ...
;         la = __builtin_amdgcn_mfma_f32_16x16x32_f16(ones, pfa, la, 0, 0, 0); lb = __builtin_amdgcn_mfma_f32_16x16x32_f16(ones, pfb, lb, 0, 0, 0);
; #pragma unroll
;         for (int dt = 0; dt < 4; ++dt) {
;             const h16x8 fa = cat8(fal[dt], fah[dt]);
;             const h16x8 fb = SHARED ? fa : cat8(fbl[dt], fbh[dt]);
;             oa[dt] = __builtin_amdgcn_mfma_f32_16x16x32_f16(fa, pfa, oa[dt], 0, 0, 0);
;             ob[dt] = __builtin_amdgcn_mfma_f32_16x16x32_f16(fb, pfb, ob[dt], 0, 0, 0);
;         }
;     }
;     lsa_out = la[0]; lsb_out = lb[0];
; template <bool ENGINE, int ESTEPS>
; __device__ __forceinline__ void moba_sparse(const Frame& F, const Args& a, int rep) {
;     ...
;                 const float ila = 1.0f / lsa, ilb = 1.0f / lsb;
;                 if (!ENGINE) { asm volatile("" :: "v"(lsa), "v"(lsb), "v"(oa[0][0]), "v"(ob[0][0])); }
;                 { const size_t pia = ((size_t)bh * SEQ + ta) * 3 + (cea & 3u), pib = ((size_t)bh * SEQ + tb) * 3 + (ceb & 3u);
;                   u32x4 sa[2], sb[2];
; #pragma unroll
;                   for (int pr = 0; pr < 2; ++pr) { const int dt0 = 2 * pr; u32x2 x, y;
;                       x.x = pkh(oa[dt0][0] * ila, oa[dt0][1] * ila); x.y = pkh(oa[dt0][2] * ila, oa[dt0][3] * ila); y.x = pkh(oa[dt0 + 1][0] * ila, oa[dt0 + 1][1] * ila); y.y = pkh(oa[dt0 + 1][2] * ila, oa[dt0 + 1][3] * ila); sa[pr] = pair16(x, y);
;                       x.x = pkh(ob[dt0][0] * ilb, ob[dt0][1] * ilb); x.y = pkh(ob[dt0][2] * ilb, ob[dt0][3] * ilb); y.x = pkh(ob[dt0 + 1][0] * ilb, ob[dt0 + 1][1] * ilb); y.y = pkh(ob[dt0 + 1][2] * ilb, ob[dt0 + 1][3] * ilb); sb[pr] = pair16(x, y); }
;                   if (va && ENGINE) { *(u32x4*)(PO + pia * HD + pair16_dim(G, 0)) = sa[0]; *(u32x4*)(PO + pia * HD + pair16_dim(G, 2)) = sa[1]; if (G == 0) PL[pia] = lsa; }
;                   if (vb && ENGINE) { *(u32x4*)(PO + pib * HD + pair16_dim(G, 0)) = sb[0]; *(u32x4*)(PO + pib * HD + pair16_dim(G, 2)) = sb[1]; if (G == 0) PL[pib] = lsb; } }
	v_mfma_f32_16x16x32_f16 v[70:73], v[166:169], v[170:173], v[70:73]
	v_mfma_f32_16x16x32_f16 v[122:125], v[166:169], v[174:177], v[122:125]
	ds_read_b64_tr_b16 v[154:155], v46 offset:61440
	ds_read_b64_tr_b16 v[156:157], v46 offset:63488
	ds_read_b64_tr_b16 v[158:159], v112 offset:61440
	ds_read_b64_tr_b16 v[160:161], v112 offset:63488
	ds_read_b64_tr_b16 v[162:163], v113 offset:61440
	ds_read_b64_tr_b16 v[164:165], v113 offset:63488
	ds_read_b64_tr_b16 v[166:167], v114 offset:61440
	ds_read_b64_tr_b16 v[168:169], v114 offset:63488
	v_mfma_f32_16x16x32_f16 v[142:145], v[34:37], v[170:173], v[142:145]
	v_mfma_f32_16x16x32_f16 v[118:121], v[34:37], v[174:177], v[118:121]
	s_waitcnt lgkmcnt(8)
	v_mfma_f32_16x16x32_f16 v[170:173], v[198:201], v[18:21], v[38:41]
	v_mfma_f32_16x16x32_f16 v[174:177], v[198:201], v[26:29], v[42:45]
	v_mfma_f32_16x16x32_f16 v[18:21], v[194:197], v[18:21], v[38:41]
	v_mfma_f32_16x16x32_f16 v[26:29], v[194:197], v[26:29], v[42:45]
	v_mfma_f32_16x16x32_f16 v[38:41], v[190:193], v[22:25], v[170:173]
	v_mfma_f32_16x16x32_f16 v[18:21], v[186:189], v[22:25], v[18:21]
	v_mfma_f32_16x16x32_f16 v[22:25], v[186:189], v[30:33], v[26:29]
	v_mfma_f32_16x16x32_f16 v[42:45], v[190:193], v[30:33], v[174:177]
	s_nop 4
	v_exp_f32_e32 v26, v38
	v_exp_f32_e32 v18, v18
	v_exp_f32_e32 v28, v22
	v_exp_f32_e32 v22, v39
	v_exp_f32_e32 v19, v19
	v_exp_f32_e32 v30, v23
	v_exp_f32_e32 v23, v40
	v_exp_f32_e32 v20, v20
	v_exp_f32_e32 v32, v24
	v_exp_f32_e32 v24, v41
	v_exp_f32_e32 v21, v21
	v_exp_f32_e32 v27, v42
	v_exp_f32_e32 v29, v43
	v_exp_f32_e32 v31, v44
	v_exp_f32_e32 v33, v45
	v_exp_f32_e32 v38, v25
	v_cvt_pk_f16_f32 v22, v26, v22
	v_cvt_pk_f16_f32 v23, v23, v24
	v_cvt_pk_f16_f32 v24, v18, v19
	v_cvt_pk_f16_f32 v25, v20, v21
	v_cvt_pk_f16_f32 v26, v27, v29
	v_cvt_pk_f16_f32 v27, v31, v33
	v_mfma_f32_16x16x32_f16 v[18:21], v[34:37], v[22:25], v[142:145]
	v_cvt_pk_f16_f32 v28, v28, v30
	v_cvt_pk_f16_f32 v29, v32, v38
	s_waitcnt lgkmcnt(6)
	v_mfma_f32_16x16x32_f16 v[30:33], v[154:157], v[22:25], v[146:149]
	v_mfma_f32_16x16x32_f16 v[38:41], v[154:157], v[26:29], v[126:129]
	s_nop 2
	v_div_scale_f32 v19, s[42:43], v18, v18, 1.0
	s_waitcnt lgkmcnt(4)
	v_mfma_f32_16x16x32_f16 v[42:45], v[158:161], v[22:25], v[138:141]
	v_mfma_f32_16x16x32_f16 v[126:129], v[158:161], v[26:29], v[130:133]
	s_waitcnt lgkmcnt(2)
	v_mfma_f32_16x16x32_f16 v[130:133], v[162:165], v[22:25], v[150:153]
	s_waitcnt lgkmcnt(0)
	v_mfma_f32_16x16x32_f16 v[70:73], v[166:169], v[22:25], v[70:73]
	v_mfma_f32_16x16x32_f16 v[20:23], v[34:37], v[26:29], v[118:121]
	v_mfma_f32_16x16x32_f16 v[134:137], v[162:165], v[26:29], v[134:137]
	v_mfma_f32_16x16x32_f16 v[122:125], v[166:169], v[26:29], v[122:125]
	s_nop 5
	v_rcp_f32_e32 v21, v19
	s_nop 0
	v_fma_f32 v22, -v19, v21, 1.0
	v_fmac_f32_e32 v21, v22, v21
	v_div_scale_f32 v22, vcc, 1.0, v18, 1.0
	v_mul_f32_e32 v23, v22, v21
	v_fma_f32 v24, -v19, v23, v22
	v_fmac_f32_e32 v23, v24, v21
	v_fma_f32 v19, -v19, v23, v22
	v_div_fmas_f32 v19, v19, v21, v23
	v_div_fixup_f32 v46, v19, v18, 1.0
	v_div_scale_f32 v19, s[42:43], v20, v20, 1.0
	v_rcp_f32_e32 v21, v19
	s_nop 0
	v_fma_f32 v22, -v19, v21, 1.0
	v_fmac_f32_e32 v21, v22, v21
	v_div_scale_f32 v22, vcc, 1.0, v20, 1.0
	v_mul_f32_e32 v23, v22, v21
	v_fma_f32 v24, -v19, v23, v22
	v_fmac_f32_e32 v23, v24, v21
	v_fma_f32 v19, -v19, v23, v22
	v_div_fmas_f32 v19, v19, v21, v23
	v_pk_mul_f32 v[22:23], v[46:47], v[30:31] op_sel_hi:[0,1]
	v_cvt_pk_f16_f32 v26, v22, v23
	v_pk_mul_f32 v[22:23], v[46:47], v[32:33] op_sel_hi:[0,1]
	v_cvt_pk_f16_f32 v27, v22, v23
	v_pk_mul_f32 v[22:23], v[46:47], v[42:43] op_sel_hi:[0,1]
	v_div_fixup_f32 v74, v19, v20, 1.0
	v_cvt_pk_f16_f32 v28, v22, v23
	v_pk_mul_f32 v[22:23], v[46:47], v[44:45] op_sel_hi:[0,1]
	v_cvt_pk_f16_f32 v29, v22, v23
	v_pk_mul_f32 v[22:23], v[38:39], v[74:75] op_sel_hi:[1,0]
	v_pk_mul_f32 v[24:25], v[40:41], v[74:75] op_sel_hi:[1,0]
	v_cvt_pk_f16_f32 v22, v22, v23
	v_cvt_pk_f16_f32 v23, v24, v25
	v_pk_mul_f32 v[24:25], v[126:127], v[74:75] op_sel_hi:[1,0]
	v_pk_mul_f32 v[30:31], v[128:129], v[74:75] op_sel_hi:[1,0]
	v_cvt_pk_f16_f32 v24, v24, v25
	v_cvt_pk_f16_f32 v25, v30, v31
	v_pk_mul_f32 v[30:31], v[46:47], v[130:131] op_sel_hi:[0,1]
	v_cvt_pk_f16_f32 v34, v30, v31
	v_pk_mul_f32 v[30:31], v[46:47], v[132:133] op_sel_hi:[0,1]
	v_cvt_pk_f16_f32 v35, v30, v31
	v_pk_mul_f32 v[30:31], v[46:47], v[70:71] op_sel_hi:[0,1]
	v_cvt_pk_f16_f32 v36, v30, v31
	v_pk_mul_f32 v[30:31], v[46:47], v[72:73] op_sel_hi:[0,1]
	v_cvt_pk_f16_f32 v37, v30, v31
	v_pk_mul_f32 v[30:31], v[134:135], v[74:75] op_sel_hi:[1,0]
	v_pk_mul_f32 v[32:33], v[136:137], v[74:75] op_sel_hi:[1,0]
	v_cvt_pk_f16_f32 v30, v30, v31
	v_cvt_pk_f16_f32 v31, v32, v33
	v_pk_mul_f32 v[32:33], v[122:123], v[74:75] op_sel_hi:[1,0]
	v_pk_mul_f32 v[38:39], v[124:125], v[74:75] op_sel_hi:[1,0]
	v_cvt_pk_f16_f32 v32, v32, v33
	v_cvt_pk_f16_f32 v33, v38, v39
	v_permlane16_swap_b32_e32 v26, v28
	v_permlane16_swap_b32_e32 v27, v29
	v_permlane16_swap_b32_e32 v22, v24
	v_permlane16_swap_b32_e32 v23, v25
	v_permlane16_swap_b32_e32 v34, v36
	v_permlane16_swap_b32_e32 v35, v37
	v_permlane16_swap_b32_e32 v30, v32
	v_permlane16_swap_b32_e32 v31, v33
	s_waitcnt vmcnt(0)
	s_and_saveexec_b64 s[54:55], s[52:53]
	s_cbranch_execz .LBB0_1152
	v_lshrrev_b32_e32 v46, 2, v106
	v_lshl_add_u64 v[40:41], s[0:1], 0, v[46:47]
	v_and_b32_e32 v46, 3, v106
	v_mad_u64_u32 v[38:39], s[42:43], v40, 3, v[46:47]
	v_mad_i32_i24 v39, v41, 3, v39
	v_lshlrev_b64 v[40:41], 7, v[38:39]
	v_lshl_add_u64 v[40:41], v[62:63], 0, v[40:41]
	global_store_dwordx4 v[40:41], v[26:29], off
	global_store_dwordx4 v[40:41], v[34:37], off offset:64
	s_and_b64 exec, exec, s[10:11]
	s_cbranch_execz .LBB0_1152
	v_lshl_add_u64 v[26:27], v[38:39], 2, s[62:63]
	global_store_dword v[26:27], v18, off

; template <bool ENGINE, int ESTEPS>
; __device__ __forceinline__ void moba_sparse(const Frame& F, const Args& a, int rep) {
;     ...
;             for (int k = 0; k < npairs; ++k) {
;                 const int nwk = k ? nw1 : nw0;
;                 const bool va = fr < nwk, vb = 16 + fr < nwk; const unsigned cea = ea, ceb = eb;
;                 const int ta = (int)(cea >> 2), tb = (int)(ceb >> 2);
;                 h16x8 qa0, qa1, qb0, qb1; float mba, mbb;
;                 moba_finish_q(ra0, ra1, maxgk, qa0, qa1, mba); moba_finish_q(rb0, rb1, maxgk, qb0, qb1, mbb);
;                 if (k + 1 < npairs) {
;                     ea = (unsigned)__shfl((int)ment, 32 + (fr < nw1 ? fr : nw1 - 1)); eb = (unsigned)__shfl((int)ment, 32 + (16 + fr < nw1 ? 16 + fr : nw1 - 1));
;                     const f16_t* pa = P + (size_t)(b * SEQ + (int)(ea >> 2)) * NB + h * HD + 8 * G; const f16_t* pb = P + (size_t)(b * SEQ + (int)(eb >> 2)) * NB + h * HD + 8 * G;
;                     ra0 = *(const h16x8*)pa; ra1 = *(const h16x8*)(pa + 32); rb0 = *(const h16x8*)pb; rb1 = *(const h16x8*)(pb + 32); }
;                 else { done_pf = true; if (it_nxt < TI) sp_prefetch(it_nxt, bh, IP, NJ, cum, offs, LIST, P, F.lds + (cb ^ 1) * 65536, w, lane, tid, pf); }
;                 f32x4 oa[4], ob[4]; float lsa = 0.f, lsb = 0.f;
; #pragma unroll
;                 for (int dt = 0; dt < 4; ++dt) { oa[dt] = (f32x4){0.f, 0.f, 0.f, 0.f}; ob[dt] = oa[dt]; }
;                 if (ENGINE || ESTEPS > 0) attn_tile2<false, true>(Kimg, Vimg, Kimg, Vimg, ENGINE ? MOBA_BLK / 32 : ESTEPS, qa0, qa1, mba, 0, qb0, qb1, mbb, 0, oa, ob, lsa, lsb, lane); else { lsa = mba; lsb = mbb; oa[0][0] = (float)qa0[0] + (float)qa1[1]; ob[0][0] = (float)qb0[0] + (float)qb1[1]; }
;                 const float ila = 1.0f / lsa, ilb = 1.0f / lsb;
;                 if (!ENGINE) { asm volatile("" :: "v"(lsa), "v"(lsb), "v"(oa[0][0]), "v"(ob[0][0])); }
;                 { const size_t pia = ((size_t)bh * SEQ + ta) * 3 + (cea & 3u), pib = ((size_t)bh * SEQ + tb) * 3 + (ceb & 3u);
;                   u32x4 sa[2], sb[2];
; #pragma unroll
;                   for (int pr = 0; pr < 2; ++pr) { const int dt0 = 2 * pr; u32x2 x, y;
.LBB0_1155:
	s_or_b64 exec, exec, s[52:53]
	s_cmp_eq_u32 s39, s36
	s_cbranch_scc1 .LBB0_1157
	v_mov_b32_e32 v106, v116
	v_mov_b32_e32 v105, v115
	s_mov_b32 s69, s39
	s_mov_b64 s[52:53], s[8:9]
	v_mov_b32_e32 v19, v69
	v_mov_b32_e32 v18, v68
	s_mov_b32 s41, s40
	s_branch .Lp8_pair_top
.LBB0_1157:
	v_mov_b32_e32 v19, v69
	v_mov_b32_e32 v18, v68
	s_mov_b32 s41, s40
	s_branch .LBB0_1159

; template <bool ENGINE, int ESTEPS>
; __device__ __forceinline__ void moba_sparse(const Frame& F, const Args& a, int rep) {
;     ...
;             if (!done_pf && it_nxt < TI) sp_prefetch(it_nxt, bh, IP, NJ, cum, offs, LIST, P, F.lds + (cb ^ 1) * 65536, w, lane, tid, pf);
;             if (tid == 0) itq[0] = (int)nn;
;             cb ^= 1;
.LBB0_1167:
	s_and_saveexec_b64 s[6:7], s[2:3]
	s_cbranch_execz .LBB0_1123
	s_waitcnt vmcnt(0)
	v_readfirstlane_b32 s34, v240
	s_nop 1
	v_add_u32_e32 v103, s34, v241
	v_mov_b32_e32 v20, s16
	ds_write_b32 v20, v103
	s_branch .LBB0_1123

; __device__ __forceinline__ unsigned pk8(float a, float b, float c, float d) { int w = __builtin_amdgcn_cvt_pk_fp8_f32(a, b, 0, false); w = __builtin_amdgcn_cvt_pk_fp8_f32(c, d, w, true); return (unsigned)w; }
; __device__ __forceinline__ int pair16_dim(int G, int dt0) { return (G & 1) ? 16 * (dt0 + 1) + 4 * (G - 1) : 16 * dt0 + 4 * G; }
; __device__ __forceinline__ void store_o8(unsigned char* rowp, const f32x4 (&o)[4], float il, int G) {
;     const float c = il * F8_SY;
; #pragma unroll
;     for (int pr = 0; pr < 2; ++pr) { const int dt0 = 2 * pr;
;         const unsigned a = pk8(o[dt0][0] * c, o[dt0][1] * c, o[dt0][2] * c, o[dt0][3] * c), b = pk8(o[dt0 + 1][0] * c, o[dt0 + 1][1] * c, o[dt0 + 1][2] * c, o[dt0 + 1][3] * c);
;         const auto r = __builtin_amdgcn_permlane16_swap(a, b, false, false);
;         *(u32x2*)(rowp + pair16_dim(G, dt0)) = (u32x2){r[0], r[1]}; }
; template <bool PR_ENG, bool PR_PART, bool PR_ST>
; __device__ __forceinline__ void moba_own(const Frame& F, const Args& a) {
;     ...
;             const float ila = 1.0f / lsa, ilb = 1.0f / lsb;
;             if (PR_ST) { store_o8((unsigned char*)Y + (size_t)(b * SEQ + ta) * DM + h * HD, oa, ila, G); store_o8((unsigned char*)Y + (size_t)(b * SEQ + tb) * DM + h * HD, ob, ilb, G); }
.LBB0_1223:
	v_div_scale_f32 v84, s[0:1], v82, v82, 1.0
	v_rcp_f32_e32 v85, v84
	v_div_scale_f32 v86, vcc, 1.0, v82, 1.0
	s_add_i32 s51, s51, s88
	v_fma_f32 v87, -v84, v85, 1.0
	v_fmac_f32_e32 v85, v87, v85
	v_mul_f32_e32 v87, v86, v85
	v_fma_f32 v88, -v84, v87, v86
	v_fmac_f32_e32 v87, v88, v85
	v_fma_f32 v84, -v84, v87, v86
	v_div_scale_f32 v86, s[0:1], v83, v83, 1.0
	v_rcp_f32_e32 v88, v86
	v_div_fmas_f32 v84, v84, v85, v87
	v_div_fixup_f32 v82, v84, v82, 1.0
	v_mul_f32_e32 v82, 0x42000000, v82
	v_fma_f32 v84, -v86, v88, 1.0
	v_fmac_f32_e32 v88, v84, v88
	v_div_scale_f32 v84, vcc, 1.0, v83, 1.0
	v_mul_f32_e32 v85, v84, v88
	v_fma_f32 v87, -v86, v85, v84
	v_fmac_f32_e32 v85, v87, v88
	v_fma_f32 v84, -v86, v85, v84
	v_div_fmas_f32 v84, v84, v88, v85
	v_mul_f32_e32 v85, v82, v18
	v_mul_f32_e32 v19, v82, v19
	v_mov_b32_e32 v18, v163
	v_cvt_pk_fp8_f32 v18, v85, v19
	v_mul_f32_e32 v22, v82, v22
	v_mul_f32_e32 v23, v82, v23
	v_mov_b32_e32 v19, v163
	v_cvt_pk_fp8_f32 v19, v22, v23
	v_mul_f32_e32 v20, v82, v20
	v_mul_f32_e32 v21, v82, v21
	v_cvt_pk_fp8_f32 v18, v20, v21 op_sel:[0,0,1]
	v_mul_f32_e32 v20, v82, v24
	v_mul_f32_e32 v21, v82, v25
	v_cvt_pk_fp8_f32 v19, v20, v21 op_sel:[0,0,1]
	v_lshlrev_b64 v[20:21], 10, v[188:189]
	v_div_fixup_f32 v24, v84, v83, 1.0
	v_lshl_add_u64 v[20:21], v[186:187], 0, v[20:21]
	v_permlane16_swap_b32_e32 v18, v19
	global_store_dwordx2 v[20:21], v[18:19], off sc1
	v_mul_f32_e32 v18, 0x42000000, v24
	v_mul_f32_e32 v19, v18, v2
	v_mul_f32_e32 v3, v18, v3
	v_mov_b32_e32 v2, v163
	v_cvt_pk_fp8_f32 v2, v19, v3
	v_mul_f32_e32 v4, v18, v4
	v_mul_f32_e32 v5, v18, v5
	v_mul_f32_e32 v6, v18, v6
	v_mul_f32_e32 v7, v18, v7
	v_mov_b32_e32 v3, v163
	v_mul_f32_e32 v23, v82, v26
	v_mul_f32_e32 v25, v82, v27
	v_mov_b32_e32 v22, v163
	v_cvt_pk_fp8_f32 v3, v6, v7
	v_cvt_pk_fp8_f32 v2, v4, v5 op_sel:[0,0,1]
	v_mul_f32_e32 v4, v18, v8
	v_mul_f32_e32 v7, v18, v10
	v_mul_f32_e32 v8, v18, v11
	v_mov_b32_e32 v6, v163
	v_mul_f32_e32 v26, v82, v28
	v_cvt_pk_fp8_f32 v22, v23, v25
	v_mul_f32_e32 v25, v82, v30
	v_mul_f32_e32 v28, v82, v31
	v_mov_b32_e32 v23, v163
	v_cvt_pk_fp8_f32 v6, v7, v8
	v_mul_f32_e32 v8, v18, v14
	v_mul_f32_e32 v11, v18, v15
	v_mov_b32_e32 v7, v163
	v_cvt_pk_fp8_f32 v23, v25, v28
	v_cvt_pk_fp8_f32 v7, v8, v11
	v_mul_f32_e32 v27, v82, v29
	v_mul_f32_e32 v5, v18, v9
	v_mul_f32_e32 v9, v18, v12
	v_mul_f32_e32 v10, v18, v13
	v_cvt_pk_fp8_f32 v22, v26, v27 op_sel:[0,0,1]
	v_mul_f32_e32 v25, v82, v32
	v_mul_f32_e32 v26, v82, v33
	v_cvt_pk_fp8_f32 v6, v9, v10 op_sel:[0,0,1]
	v_mul_f32_e32 v8, v18, v16
	v_mul_f32_e32 v9, v18, v17
	v_cvt_pk_fp8_f32 v23, v25, v26 op_sel:[0,0,1]
	v_cvt_pk_fp8_f32 v3, v4, v5 op_sel:[0,0,1]
	v_cvt_pk_fp8_f32 v7, v8, v9 op_sel:[0,0,1]
	v_lshlrev_b64 v[4:5], 10, v[190:191]
	v_permlane16_swap_b32_e32 v22, v23
	v_permlane16_swap_b32_e32 v2, v3
	v_lshl_add_u64 v[4:5], v[186:187], 0, v[4:5]
	v_permlane16_swap_b32_e32 v6, v7
	s_cmpk_lt_i32 s51, 0x300
	global_store_dwordx2 v[20:21], v[22:23], off offset:32 sc1
	global_store_dwordx2 v[4:5], v[2:3], off sc1
	global_store_dwordx2 v[4:5], v[6:7], off offset:32 sc1
	s_cbranch_scc0 .LBB0_1259

; __device__ __forceinline__ unsigned pk8(float a, float b, float c, float d) { int w = __builtin_amdgcn_cvt_pk_fp8_f32(a, b, 0, false); w = __builtin_amdgcn_cvt_pk_fp8_f32(c, d, w, true); return (unsigned)w; }
; __device__ __forceinline__ int pair16_dim(int G, int dt0) { return (G & 1) ? 16 * (dt0 + 1) + 4 * (G - 1) : 16 * dt0 + 4 * G; }
; __device__ __forceinline__ void store_o8(unsigned char* rowp, const f32x4 (&o)[4], float il, int G) {
;     const float c = il * F8_SY;
; #pragma unroll
;     for (int pr = 0; pr < 2; ++pr) { const int dt0 = 2 * pr;
;         const unsigned a = pk8(o[dt0][0] * c, o[dt0][1] * c, o[dt0][2] * c, o[dt0][3] * c), b = pk8(o[dt0 + 1][0] * c, o[dt0 + 1][1] * c, o[dt0 + 1][2] * c, o[dt0 + 1][3] * c);
;         const auto r = __builtin_amdgcn_permlane16_swap(a, b, false, false);
;         *(u32x2*)(rowp + pair16_dim(G, dt0)) = (u32x2){r[0], r[1]}; }
; __device__ __forceinline__ void moba_load_q(const f16_t* qrow, int G, float maxgk, h16x8& q0, h16x8& q1, float& mb) {
;     const h16x8 r0v = *(const h16x8*)(qrow + 8 * G), r1v = *(const h16x8*)(qrow + 32 + 8 * G);
;     float q[16], n2 = 0.f;
; #pragma unroll
;     for (int j = 0; j < 8; ++j) { q[j] = (float)r0v[j]; q[8 + j] = (float)r1v[j]; n2 += q[j] * q[j] + q[8 + j] * q[8 + j]; }
;     n2 += __shfl_xor(n2, 16); n2 += __shfl_xor(n2, 32);
.LBB0_1240:
	s_nop 0
	v_div_scale_f32 v32, s[24:25], v30, v30, 1.0
	v_rcp_f32_e32 v33, v32
	v_lshl_add_u64 v[186:187], v[164:165], 0, s[22:23]
	v_add_u32_e32 v192, s54, v200
	v_or_b32_e32 v194, 16, v192
	v_fma_f32 v86, -v32, v33, 1.0
	v_fmac_f32_e32 v33, v86, v33
	v_div_scale_f32 v86, vcc, 1.0, v30, 1.0
	v_mul_f32_e32 v87, v86, v33
	v_fma_f32 v88, -v32, v87, v86
	v_fmac_f32_e32 v87, v88, v33
	v_fma_f32 v32, -v32, v87, v86
	v_div_scale_f32 v86, s[22:23], v31, v31, 1.0
	v_rcp_f32_e32 v88, v86
	v_div_fmas_f32 v32, v32, v33, v87
	v_div_fixup_f32 v30, v32, v30, 1.0
	v_mul_f32_e32 v30, 0x42000000, v30
	v_fma_f32 v32, -v86, v88, 1.0
	v_fmac_f32_e32 v88, v32, v88
	v_div_scale_f32 v32, vcc, 1.0, v31, 1.0
	v_mul_f32_e32 v33, v32, v88
	v_fma_f32 v87, -v86, v33, v32
	v_fmac_f32_e32 v33, v87, v88
	v_fma_f32 v32, -v86, v33, v32
	v_div_fmas_f32 v86, v32, v88, v33
	v_mul_f32_e32 v33, v30, v82
	v_mul_f32_e32 v82, v30, v83
	v_mov_b32_e32 v32, 0
	v_cvt_pk_fp8_f32 v32, v33, v82
	v_mul_f32_e32 v26, v30, v26
	v_mul_f32_e32 v27, v30, v27
	v_mov_b32_e32 v33, 0
	v_cvt_pk_fp8_f32 v33, v26, v27
	v_mul_f32_e32 v27, v30, v29
	v_mul_f32_e32 v29, v30, v22
	v_mul_f32_e32 v23, v30, v23
	v_mov_b32_e32 v22, 0
	v_mul_f32_e32 v26, v30, v28
	v_div_fixup_f32 v28, v86, v31, 1.0
	v_cvt_pk_fp8_f32 v22, v29, v23
	v_mul_f32_e32 v18, v30, v18
	v_mul_f32_e32 v19, v30, v19
	v_mov_b32_e32 v23, 0
	v_cvt_pk_fp8_f32 v23, v18, v19
	v_mul_f32_e32 v18, v30, v20
	v_mul_f32_e32 v20, 0x42000000, v28
	v_mul_f32_e32 v19, v30, v21
	v_mul_f32_e32 v21, v20, v14
	v_mul_f32_e32 v15, v20, v15
	v_mov_b32_e32 v14, 0
	v_cvt_pk_fp8_f32 v14, v21, v15
	v_mul_f32_e32 v10, v20, v10
	v_mul_f32_e32 v11, v20, v11
	v_mov_b32_e32 v15, 0
	v_cvt_pk_fp8_f32 v15, v10, v11
	v_mul_f32_e32 v10, v20, v12
	v_mul_f32_e32 v12, v20, v6
	v_mul_f32_e32 v7, v20, v7
	v_mov_b32_e32 v6, 0
	v_cvt_pk_fp8_f32 v6, v12, v7
	v_mul_f32_e32 v2, v20, v2
	v_mul_f32_e32 v3, v20, v3
	v_mov_b32_e32 v7, 0
	v_cvt_pk_fp8_f32 v7, v2, v3
	v_mul_f32_e32 v16, v20, v16
	v_mul_f32_e32 v17, v20, v17
	v_mul_f32_e32 v11, v20, v13
	v_mul_f32_e32 v8, v20, v8
	v_mul_f32_e32 v9, v20, v9
	v_mul_f32_e32 v2, v20, v4
	v_mul_f32_e32 v3, v20, v5
	v_mul_f32_e32 v83, v30, v84
	v_mul_f32_e32 v84, v30, v85
	v_mul_f32_e32 v24, v30, v24
	v_mul_f32_e32 v25, v30, v25
	v_cvt_pk_fp8_f32 v14, v16, v17 op_sel:[0,0,1]
	v_cvt_pk_fp8_f32 v15, v10, v11 op_sel:[0,0,1]
	v_cvt_pk_fp8_f32 v6, v8, v9 op_sel:[0,0,1]
	v_cvt_pk_fp8_f32 v7, v2, v3 op_sel:[0,0,1]
	v_cvt_pk_fp8_f32 v32, v83, v84 op_sel:[0,0,1]
	v_cvt_pk_fp8_f32 v33, v26, v27 op_sel:[0,0,1]
	v_cvt_pk_fp8_f32 v22, v24, v25 op_sel:[0,0,1]
	v_cvt_pk_fp8_f32 v23, v18, v19 op_sel:[0,0,1]
	v_lshlrev_b64 v[10:11], 10, v[190:191]
	v_lshlrev_b64 v[26:27], 10, v[188:189]
	v_permlane16_swap_b32_e32 v14, v15
	v_lshl_add_u64 v[2:3], v[186:187], 0, v[10:11]
	v_permlane16_swap_b32_e32 v6, v7
	v_add_u32_e32 v188, s53, v192
	v_permlane16_swap_b32_e32 v32, v33
	v_lshl_add_u64 v[18:19], v[186:187], 0, v[26:27]
	v_permlane16_swap_b32_e32 v22, v23
	global_store_dwordx2 v[2:3], v[14:15], off sc1
	global_store_dwordx2 v[2:3], v[6:7], off offset:32 sc1
	global_store_dwordx2 v[18:19], v[32:33], off sc1
	global_store_dwordx2 v[18:19], v[22:23], off offset:32 sc1
	v_add_u32_e32 v190, s53, v194
	s_andn2_b64 vcc, exec, s[12:13]
	s_mov_b32 s22, 0
	v_cvt_f32_f16_e32 v32, v240
	v_cvt_f32_f16_e32 v24, v244
	v_cvt_f32_f16_sdwa v25, v244 dst_sel:DWORD dst_unused:UNUSED_PAD src0_sel:WORD_1
	v_cvt_f32_f16_sdwa v33, v240 dst_sel:DWORD dst_unused:UNUSED_PAD src0_sel:WORD_1
	v_cvt_f32_f16_e32 v22, v245
	v_cvt_f32_f16_sdwa v23, v245 dst_sel:DWORD dst_unused:UNUSED_PAD src0_sel:WORD_1
	v_cvt_f32_f16_e32 v30, v241
	v_cvt_f32_f16_sdwa v31, v241 dst_sel:DWORD dst_unused:UNUSED_PAD src0_sel:WORD_1
	v_cvt_f32_f16_e32 v14, v246
	v_cvt_f32_f16_sdwa v15, v246 dst_sel:DWORD dst_unused:UNUSED_PAD src0_sel:WORD_1
	v_cvt_f32_f16_e32 v28, v242
	v_cvt_f32_f16_sdwa v29, v242 dst_sel:DWORD dst_unused:UNUSED_PAD src0_sel:WORD_1
	v_pk_mul_f32 v[2:3], v[24:25], v[24:25]
	v_cvt_f32_f16_e32 v26, v243
	v_cvt_f32_f16_sdwa v27, v243 dst_sel:DWORD dst_unused:UNUSED_PAD src0_sel:WORD_1
	v_pk_fma_f32 v[4:5], v[32:33], v[32:33], v[2:3]
	v_pk_mul_f32 v[6:7], v[22:23], v[22:23]
	v_cvt_f32_f16_e32 v2, v247
	v_cvt_f32_f16_sdwa v3, v247 dst_sel:DWORD dst_unused:UNUSED_PAD src0_sel:WORD_1
	v_pk_fma_f32 v[6:7], v[30:31], v[30:31], v[6:7]
	v_add_f32_e32 v4, v4, v5
	v_pk_mul_f32 v[8:9], v[14:15], v[14:15]
	v_add_f32_e32 v4, v6, v4
	v_pk_fma_f32 v[8:9], v[28:29], v[28:29], v[8:9]
	v_add_f32_e32 v4, v7, v4
	v_pk_mul_f32 v[10:11], v[2:3], v[2:3]
	v_add_f32_e32 v4, v8, v4
	v_pk_fma_f32 v[10:11], v[26:27], v[26:27], v[10:11]
	v_add_f32_e32 v4, v9, v4
	v_add_f32_e32 v4, v10, v4
	v_add_f32_e32 v90, v11, v4
	v_cvt_f32_f16_e32 v10, v252
	v_cvt_f32_f16_sdwa v11, v252 dst_sel:DWORD dst_unused:UNUSED_PAD src0_sel:WORD_1
	v_cvt_f32_f16_e32 v6, v248
	v_cvt_f32_f16_sdwa v7, v248 dst_sel:DWORD dst_unused:UNUSED_PAD src0_sel:WORD_1
	v_cvt_f32_f16_e32 v20, v253
	v_cvt_f32_f16_sdwa v21, v253 dst_sel:DWORD dst_unused:UNUSED_PAD src0_sel:WORD_1
	v_cvt_f32_f16_e32 v8, v249
	v_cvt_f32_f16_sdwa v9, v249 dst_sel:DWORD dst_unused:UNUSED_PAD src0_sel:WORD_1
	v_cvt_f32_f16_e32 v16, v254
	v_cvt_f32_f16_sdwa v17, v254 dst_sel:DWORD dst_unused:UNUSED_PAD src0_sel:WORD_1
	v_cvt_f32_f16_e32 v12, v250
	v_cvt_f32_f16_sdwa v13, v250 dst_sel:DWORD dst_unused:UNUSED_PAD src0_sel:WORD_1
	v_pk_mul_f32 v[4:5], v[10:11], v[10:11]
	v_pk_mul_f32 v[86:87], v[20:21], v[20:21]
	v_pk_fma_f32 v[82:83], v[6:7], v[6:7], v[4:5]
	v_cvt_f32_f16_e32 v4, v255
	v_cvt_f32_f16_sdwa v5, v255 dst_sel:DWORD dst_unused:UNUSED_PAD src0_sel:WORD_1
	v_cvt_f32_f16_e32 v18, v251
	v_cvt_f32_f16_sdwa v19, v251 dst_sel:DWORD dst_unused:UNUSED_PAD src0_sel:WORD_1
	v_pk_fma_f32 v[84:85], v[8:9], v[8:9], v[86:87]
	v_add_f32_e32 v82, v82, v83
	v_pk_mul_f32 v[86:87], v[16:17], v[16:17]
	v_add_f32_e32 v82, v84, v82
	v_pk_fma_f32 v[86:87], v[12:13], v[12:13], v[86:87]
	v_add_f32_e32 v82, v85, v82
	v_pk_mul_f32 v[88:89], v[4:5], v[4:5]
	v_add_f32_e32 v82, v86, v82
	v_pk_fma_f32 v[88:89], v[18:19], v[18:19], v[88:89]
	v_add_f32_e32 v82, v87, v82
	v_add_f32_e32 v82, v88, v82
	v_add_f32_e32 v82, v89, v82
	ds_bpermute_b32 v91, v1, v90
	ds_bpermute_b32 v83, v1, v82
	s_waitcnt lgkmcnt(1)
	v_add_f32_e32 v84, v90, v91
	s_waitcnt lgkmcnt(0)
	v_add_f32_e32 v82, v82, v83
	ds_bpermute_b32 v85, v196, v84
	ds_bpermute_b32 v83, v196, v82
	s_cbranch_vccnz .LBB0_1245
; #define LAS __attribute__((address_space(3)))
; __device__ __forceinline__ unsigned pkh(float lo, float hi) { f32x2 v = {lo, hi}; h16x2 h = __builtin_convertvector(v, h16x2); return __builtin_bit_cast(unsigned, h); }
; template <bool CAUSAL, bool SHARED> ...
;     ...
;     ka[0] = *(LAS const h16x8*)(Ka + kof0); ka[1] = *(LAS const h16x8*)(Ka + kof1); ka[2] = *(LAS const h16x8*)(Ka + 2048 + kof0); ka[3] = *(LAS const h16x8*)(Ka + 2048 + kof1);
; __device__ __forceinline__ void moba_load_q(const f16_t* qrow, int G, float maxgk, h16x8& q0, h16x8& q1, float& mb) {
;     ...
;     for (int j = 0; j < 8; ++j) { q[j] = (float)r0v[j]; q[8 + j] = (float)r1v[j]; n2 += q[j] * q[j] + q[8 + j] * q[8 + j]; }
;     n2 += __shfl_xor(n2, 16); n2 += __shfl_xor(n2, 32);
;     mb = (sqrtf(n2) * maxgk - BOUND_SHIFT) * LOG2E;
;     const float c = 0.125f * LOG2E;
;     u32x4 w0, w1;
;     w0.x = pkh(q[0] * c, q[1] * c); w0.y = pkh(q[2] * c, q[3] * c); w0.z = pkh(q[4] * c, q[5] * c); w0.w = pkh(q[6] * c, q[7] * c);
;     w1.x = pkh(q[8] * c, q[9] * c); w1.y = pkh(q[10] * c, q[11] * c); w1.z = pkh(q[12] * c, q[13] * c); w1.w = pkh(q[14] * c, q[15] * c);
;     q0 = __builtin_bit_cast(h16x8, w0); q1 = __builtin_bit_cast(h16x8, w1);
	v_pk_mul_f32 v[24:25], v[24:25], s[18:19] op_sel_hi:[1,0]
	v_pk_mul_f32 v[14:15], v[14:15], s[18:19] op_sel_hi:[1,0]
	v_cvt_pk_f16_f32 v90, v24, v25
	s_waitcnt lgkmcnt(1)
	v_add_f32_e32 v24, v84, v85
	v_mul_f32_e32 v25, 0x4f800000, v24
	v_cmp_gt_f32_e32 vcc, s31, v24
	v_pk_mul_f32 v[22:23], v[22:23], s[18:19] op_sel_hi:[1,0]
	v_cvt_pk_f16_f32 v92, v14, v15
	v_cndmask_b32_e32 v24, v24, v25, vcc
	v_sqrt_f32_e32 v25, v24
	v_cvt_pk_f16_f32 v91, v22, v23
	v_pk_mul_f32 v[2:3], v[2:3], s[18:19] op_sel_hi:[1,0]
	v_pk_mul_f32 v[32:33], v[32:33], s[18:19] op_sel_hi:[1,0]
	v_add_u32_e32 v15, -1, v25
	v_fma_f32 v22, -v15, v25, v24
	v_cmp_ge_f32_e64 s[2:3], 0, v22
	v_add_u32_e32 v22, 1, v25
	v_fma_f32 v23, -v22, v25, v24
	v_cndmask_b32_e64 v15, v25, v15, s[2:3]
	v_cmp_lt_f32_e64 s[2:3], 0, v23
	v_cvt_pk_f16_f32 v93, v2, v3
	v_pk_mul_f32 v[2:3], v[6:7], s[18:19] op_sel_hi:[1,0]
	v_cndmask_b32_e64 v15, v15, v22, s[2:3]
	v_mul_f32_e32 v22, 0x37800000, v15
	v_cndmask_b32_e32 v15, v15, v22, vcc
	v_cmp_class_f32_e32 vcc, v24, v219
	s_waitcnt lgkmcnt(0)
	v_add_f32_e32 v6, v82, v83
	v_cvt_pk_f16_f32 v94, v2, v3
	v_cndmask_b32_e32 v15, v15, v24, vcc
	v_pk_mul_f32 v[2:3], v[8:9], s[18:19] op_sel_hi:[1,0]
	v_mul_f32_e32 v7, 0x4f800000, v6
	v_cmp_gt_f32_e32 vcc, s31, v6
	v_cvt_pk_f16_f32 v95, v2, v3
	v_pk_mul_f32 v[2:3], v[12:13], s[18:19] op_sel_hi:[1,0]
	v_cndmask_b32_e32 v6, v6, v7, vcc
	v_cvt_pk_f16_f32 v96, v2, v3
	v_pk_mul_f32 v[2:3], v[18:19], s[18:19] op_sel_hi:[1,0]
	v_sqrt_f32_e32 v7, v6
	v_cvt_pk_f16_f32 v97, v2, v3
	v_pk_mul_f32 v[2:3], v[10:11], s[18:19] op_sel_hi:[1,0]
	v_fma_f32 v15, v197, v15, -4.0
	v_cvt_pk_f16_f32 v98, v2, v3
	v_pk_mul_f32 v[2:3], v[20:21], s[18:19] op_sel_hi:[1,0]
	v_pk_mul_f32 v[30:31], v[30:31], s[18:19] op_sel_hi:[1,0]
	v_cvt_pk_f16_f32 v99, v2, v3
	v_pk_mul_f32 v[2:3], v[16:17], s[18:19] op_sel_hi:[1,0]
	v_pk_mul_f32 v[28:29], v[28:29], s[18:19] op_sel_hi:[1,0]
	v_cvt_pk_f16_f32 v100, v2, v3
	v_add_u32_e32 v2, -1, v7
	v_fma_f32 v3, -v2, v7, v6
	v_cmp_ge_f32_e64 s[2:3], 0, v3
	v_add_u32_e32 v3, 1, v7
	v_pk_mul_f32 v[26:27], v[26:27], s[18:19] op_sel_hi:[1,0]
	v_cndmask_b32_e64 v2, v7, v2, s[2:3]
	v_fma_f32 v7, -v3, v7, v6
	v_cmp_lt_f32_e64 s[2:3], 0, v7
	v_mov_b32_e32 v14, 0
	v_mul_f32_e32 v102, 0xbfb8aa3b, v15
	v_cndmask_b32_e64 v2, v2, v3, s[2:3]
	v_mul_f32_e32 v3, 0x37800000, v2
	v_cndmask_b32_e32 v2, v2, v3, vcc
	v_cmp_class_f32_e32 vcc, v6, v219
	v_cvt_pk_f16_f32 v86, v32, v33
	v_cvt_pk_f16_f32 v87, v30, v31
	v_cndmask_b32_e32 v2, v2, v6, vcc
	v_fma_f32 v6, v197, v2, -4.0
	v_pk_mul_f32 v[2:3], v[4:5], s[18:19] op_sel_hi:[1,0]
	v_mul_f32_e32 v106, 0xbfb8aa3b, v6
	v_cvt_pk_f16_f32 v101, v2, v3
	v_add_u32_e32 v2, s34, v202
	v_add_u32_e32 v3, s34, v201
	ds_read_b128 v[114:117], v2
	ds_read_b128 v[110:113], v3
	v_add_u32_e32 v2, s30, v202
	v_add_u32_e32 v3, s30, v201
	ds_read_b128 v[122:125], v2
	ds_read_b128 v[118:121], v3
	v_cvt_pk_f16_f32 v88, v28, v29
	v_cvt_pk_f16_f32 v89, v26, v27
	v_mov_b32_e32 v103, v102
	v_mov_b32_e32 v104, v102
	v_mov_b32_e32 v105, v102
	v_mov_b32_e32 v107, v106
	v_mov_b32_e32 v108, v106
	v_mov_b32_e32 v109, v106
	v_mov_b32_e32 v169, v217
	v_mov_b32_e32 v171, v215
	v_mov_b32_e32 v189, v213
	v_mov_b32_e32 v191, v211
	v_mov_b32_e32 v193, v202
	v_mov_b32_e32 v195, v201
	s_mov_b32 s23, 0
	v_mov_b32_e32 v15, v14
	v_mov_b32_e32 v16, v14
	v_mov_b32_e32 v17, v14
	v_mov_b32_e32 v2, v14
	v_mov_b32_e32 v3, v14
	v_mov_b32_e32 v4, v14
	v_mov_b32_e32 v5, v14
	v_mov_b32_e32 v6, v14
	v_mov_b32_e32 v7, v14
	v_mov_b32_e32 v8, v14
	v_mov_b32_e32 v9, v14
	v_mov_b32_e32 v10, v14
	v_mov_b32_e32 v11, v14
	v_mov_b32_e32 v12, v14
	v_mov_b32_e32 v13, v14
	v_mov_b32_e32 v30, v14
	v_mov_b32_e32 v31, v14
	v_mov_b32_e32 v32, v14
	v_mov_b32_e32 v33, v14
	v_mov_b32_e32 v18, v14
	v_mov_b32_e32 v19, v14
	v_mov_b32_e32 v20, v14
	v_mov_b32_e32 v21, v14
	v_mov_b32_e32 v22, v14
	v_mov_b32_e32 v23, v14
	v_mov_b32_e32 v24, v14
	v_mov_b32_e32 v25, v14
	v_mov_b32_e32 v26, v14
	v_mov_b32_e32 v27, v14
	v_mov_b32_e32 v28, v14
	v_mov_b32_e32 v29, v14
	v_mov_b32_e32 v82, v14
	v_mov_b32_e32 v83, v14
	v_mov_b32_e32 v84, v14
	v_mov_b32_e32 v85, v14
	v_mov_b32_e32 v126, v14
	v_mov_b32_e32 v127, v14
	v_mov_b32_e32 v128, v14
	v_mov_b32_e32 v129, v14
	s_branch .LBB0_1243
